# SSD step: prefetch loads dripped early, LDS fill of the next chunk later in the step (more prefetch slack)
# baseline (speedup 1.0000x reference)
; __device__ __forceinline__ void phase_ssd(const Params& P, int seg, unsigned char* smem) {
;     ...
;         auto step = [&](int ci, Pre& R, const int par) {
;             const int row0 = chunk_row0(ci); unsigned char* sb = smem + par * T_BUF; float* acP = acS + par * 64;
;             const bf16* StR = StS + par * (T_STSZ / 2); bf16* StW = StS + (par ^ 1) * (T_STSZ / 2);
;             const float dec = __expf(R.alast);
;             { const float e2 = __expf(R.alast - R.acl);
; #pragma unroll
;               for (int i = 0; i < 2; ++i) { const int q = tid + 512 * i, l = q >> 4, c8 = q & 15; *(v4u*)(sb + T_CS + l * 272 + c8 * 16) = R.Cr[i]; *(v4u*)(sb + T_BS + l * 272 + c8 * 16) = R.Br[i]; }
;               const int l = tid >> 3, p4 = (tid & 7) * 4;
;               const float x0 = bflo(R.Xr.x) * R.dtl, x1 = bfhi(R.Xr.x) * R.dtl, x2 = bflo(R.Xr.y) * R.dtl, x3 = bfhi(R.Xr.y) * R.dtl;
;               v2u d; d.x = cvt_pk_bf16(x0, x1); d.y = cvt_pk_bf16(x2, x3); *(v2u*)(sb + T_XD + l * 80 + p4 * 2) = d;
;               v2u e; e.x = cvt_pk_bf16(x0 * e2, x1 * e2); e.y = cvt_pk_bf16(x2 * e2, x3 * e2); *(v2u*)(sb + T_XE + l * 80 + p4 * 2) = e;
;               *(v2u*)(sb + T_XS + l * 64 + p4 * 2) = R.Xr; *(v2u*)(sb + T_ZS + l * 64 + p4 * 2) = R.Zr;
;               if (w == 0) acP[lane] = R.aclane; }
;             BAR_LDS();
;             if (ci + 2 < nchunks) load_chunk(ci + 2, R);
;             bf16x8 cf[4];
; #pragma unroll
;             for (int k = 0; k < 4; ++k) cf[k] = *(const bf16x8*)(sb + T_CS + (lt * 16 + fr) * 272 + (k * 32 + fq * 8) * 2);
;             f32x4 yo = {0.f, 0.f, 0.f, 0.f};
; #pragma unroll
;             for (int k = 0; k < 4; ++k) { const bf16x8 bb = *(const bf16x8*)((const unsigned char*)StR + (pt * 16 + fr) * 272 + (k * 32 + fq * 8) * 2); yo = mfma16(cf[k], bb, yo); }
; { const f32x4 a4 = *(const f32x4*)(acP + lt * 16 + fq * 4);
; #pragma unroll
;               for (int j = 0; j < 4; ++j) yo[j] *= __expf(a4[j]); }
;             const float acl_fr = acP[lt * 16 + fr]; const int lrow = lt * 16 + fr;
; #pragma unroll
;             for (int t = 0; t < 2; ++t) {
;                 if (2 * t <= lt) {
;                     v2u xb0, xb1;
;                     { const unsigned a0 = lds0 + par * T_BUF + T_XD + (32 * t + 4 * fq + tq) * 80 + (pt * 16 + 4 * tp) * 2, a1 = a0 + 16 * 80; TR_ISSUE(xb0, a0); TR_ISSUE(xb1, a1); }
;                     float m[8];
.Lssd_loop0:
	ds_read_b128 v[28:31], v219
	ds_read_b128 v[32:35], v220
	ds_read_b128 v[40:43], v221
	ds_read_b128 v[44:47], v222
	ds_read_b128 v[48:51], v227
	ds_read_b128 v[52:55], v228
	ds_read_b128 v[56:59], v229
	ds_read_b128 v[60:63], v230
	ds_read_b32 v194, v231
	ds_read_b64_tr_b16 v[96:97], v244 offset:16384
	ds_read_b64_tr_b16 v[98:99], v244 offset:20480
	ds_read_b64_tr_b16 v[100:101], v244 offset:24576
	ds_read_b64_tr_b16 v[102:103], v244 offset:28672
	ds_read_b64_tr_b16 v[104:105], v245 offset:16384
	ds_read_b64_tr_b16 v[106:107], v245 offset:20480
	s_waitcnt lgkmcnt(11)
	ds_read_b64_tr_b16 v[108:109], v245 offset:24576
	ds_read_b64_tr_b16 v[110:111], v245 offset:28672
	ds_read_b64_tr_b16 v[112:113], v237 offset:37888
	ds_read_b64_tr_b16 v[114:115], v237 offset:39168
	s_waitcnt lgkmcnt(11)
	ds_read_b64_tr_b16 v[124:125], v237 offset:37920
	ds_read_b64_tr_b16 v[126:127], v237 offset:39200
	ds_read_b64_tr_b16 v[120:121], v237 offset:40448
	ds_read_b64_tr_b16 v[122:123], v237 offset:41728
	global_load_dwordx4 v[140:143], v204, s[40:41] offset:2048
	s_waitcnt lgkmcnt(11)
	ds_read_b64_tr_b16 v[128:129], v237 offset:40480
	ds_read_b64_tr_b16 v[130:131], v237 offset:41760
	global_load_dwordx4 v[144:147], v205, s[40:41] offset:2048
	ds_read_b128 v[64:67], v219 offset:16384
	ds_read_b128 v[68:71], v220 offset:16384
	s_waitcnt lgkmcnt(11)
	ds_read_b128 v[72:75], v221 offset:16384
	global_load_dwordx4 v[132:135], v204, s[40:41]
	ds_read_b128 v[76:79], v222 offset:16384
	v_mfma_f32_16x16x32_bf16 v[24:27], v[48:51], v[28:31], 0
	global_load_dwordx4 v[136:139], v205, s[40:41]
	v_mfma_f32_16x16x32_bf16 v[24:27], v[52:55], v[32:35], v[24:27]
	v_mfma_f32_16x16x32_bf16 v[24:27], v[56:59], v[40:43], v[24:27]
	v_mfma_f32_16x16x32_bf16 v[24:27], v[60:63], v[44:47], v[24:27]
	global_load_dwordx2 v[4:5], v206, s[40:41]
	ds_read_b64_tr_b16 v[56:57], v233 offset:32768
	ds_read_b64_tr_b16 v[58:59], v233 offset:34048
	global_load_dwordx2 v[36:37], v207, s[42:43] nt
	v_mul_f32_e32 v8, v8, v174
	v_mul_f32_e32 v9, v9, v174
	v_mul_f32_e32 v10, v10, v174
	global_load_dword v6, v208, s[44:45]
	v_mul_f32_e32 v11, v11, v174
	v_mul_f32_e32 v12, v12, v174
	v_mul_f32_e32 v13, v13, v174
	global_load_dword v116, v208, s[46:47]
	v_mul_f32_e32 v14, v14, v174
	v_mul_f32_e32 v15, v15, v174
	global_load_dword v117, v209, s[46:47]
	v_mul_f32_e32 v16, v16, v174
	v_mul_f32_e32 v17, v17, v174
	v_mul_f32_e32 v18, v18, v174
	s_add_u32 s66, s54, 3
	s_cmp_lt_u32 s66, s39
	s_cselect_b32 s74, 0xc0000, 0
	s_cselect_b32 s75, 0x280000, 0
	s_cselect_b32 s76, 0x4000, 0
	s_add_u32 s40, s40, s74
	s_addc_u32 s41, s41, 0
	s_add_u32 s42, s42, s75
	s_addc_u32 s43, s43, 0
	s_add_u32 s44, s44, s76
	s_addc_u32 s45, s45, 0
	s_add_u32 s46, s46, s76
	s_addc_u32 s47, s47, 0
	v_mul_f32_e32 v19, v19, v174
	v_mul_f32_e32 v20, v20, v174
	v_mul_f32_e32 v21, v21, v174
	v_mul_f32_e32 v22, v22, v174
	v_mul_f32_e32 v23, v23, v174
	s_waitcnt lgkmcnt(12)
	v_mfma_f32_16x16x32_bf16 v[8:11], v[96:99], v[112:115], v[8:11]
	s_waitcnt lgkmcnt(10)
	v_mfma_f32_16x16x32_bf16 v[12:15], v[96:99], v[124:127], v[12:15]
	v_mfma_f32_16x16x32_bf16 v[16:19], v[104:107], v[112:115], v[16:19]
	v_mfma_f32_16x16x32_bf16 v[20:23], v[104:107], v[124:127], v[20:23]
	s_waitcnt lgkmcnt(8)
	v_mfma_f32_16x16x32_bf16 v[8:11], v[100:103], v[120:123], v[8:11]
	s_waitcnt lgkmcnt(6)
	v_mfma_f32_16x16x32_bf16 v[12:15], v[100:103], v[128:131], v[12:15]
	v_mfma_f32_16x16x32_bf16 v[16:19], v[108:111], v[120:123], v[16:19]
	v_mfma_f32_16x16x32_bf16 v[20:23], v[108:111], v[128:131], v[20:23]
	ds_read_b128 v[96:99], v232
	ds_read_b64 v[124:125], v235 offset:43008
	ds_read_b64 v[126:127], v235 offset:47616
	s_waitcnt lgkmcnt(8)
	v_mfma_f32_16x16x32_bf16 v[48:51], v[64:67], v[28:31], 0
	s_waitcnt lgkmcnt(7)
	v_mfma_f32_16x16x32_bf16 v[48:51], v[68:71], v[32:35], v[48:51]
	s_waitcnt lgkmcnt(6)
	v_mfma_f32_16x16x32_bf16 v[48:51], v[72:75], v[40:43], v[48:51]
	s_waitcnt lgkmcnt(5)
	v_mfma_f32_16x16x32_bf16 v[48:51], v[76:79], v[44:47], v[48:51]
	v_exp_f32_e32 v195, v194
	s_nop 0
	v_mul_f32_e32 v24, v24, v195
	v_mul_f32_e32 v25, v25, v195
	v_mul_f32_e32 v26, v26, v195
	v_mul_f32_e32 v27, v27, v195
	v_cvt_pk_bf16_f32 v184, v8, v9
	v_cvt_pk_bf16_f32 v185, v10, v11
	v_cvt_pk_bf16_f32 v186, v12, v13
	v_cvt_pk_bf16_f32 v187, v14, v15
	v_cvt_pk_bf16_f32 v188, v16, v17
	v_cvt_pk_bf16_f32 v189, v18, v19
	v_cvt_pk_bf16_f32 v190, v20, v21
	v_cvt_pk_bf16_f32 v191, v22, v23
	ds_write_b64 v248, v[184:185] offset:8192
	ds_write_b64 v248, v[186:187] offset:12288
	ds_write_b64 v249, v[188:189] offset:8192
	ds_write_b64 v249, v[190:191] offset:12288
	s_waitcnt lgkmcnt(4)
	v_lshlrev_b32_e32 v112, 16, v126
	v_and_b32_e32 v113, 0xffff0000, v126
	v_lshlrev_b32_e32 v114, 16, v127
	v_and_b32_e32 v115, 0xffff0000, v127
	v_mul_f32_e32 v120, 0xbfb8aa3b, v112
	s_waitcnt vmcnt(10)
; __device__ __forceinline__ void phase_ssd(const Params& P, int seg, unsigned char* smem) {
;     ...
;         auto step = [&](int ci, Pre& R, const int par) {
;             const int row0 = chunk_row0(ci); unsigned char* sb = smem + par * T_BUF; float* acP = acS + par * 64;
;             const bf16* StR = StS + par * (T_STSZ / 2); bf16* StW = StS + (par ^ 1) * (T_STSZ / 2);
;             const float dec = __expf(R.alast);
;             { const float e2 = __expf(R.alast - R.acl);
; #pragma unroll
;               for (int i = 0; i < 2; ++i) { const int q = tid + 512 * i, l = q >> 4, c8 = q & 15; *(v4u*)(sb + T_CS + l * 272 + c8 * 16) = R.Cr[i]; *(v4u*)(sb + T_BS + l * 272 + c8 * 16) = R.Br[i]; }
;               const int l = tid >> 3, p4 = (tid & 7) * 4;
;               const float x0 = bflo(R.Xr.x) * R.dtl, x1 = bfhi(R.Xr.x) * R.dtl, x2 = bflo(R.Xr.y) * R.dtl, x3 = bfhi(R.Xr.y) * R.dtl;
;               v2u d; d.x = cvt_pk_bf16(x0, x1); d.y = cvt_pk_bf16(x2, x3); *(v2u*)(sb + T_XD + l * 80 + p4 * 2) = d;
;               v2u e; e.x = cvt_pk_bf16(x0 * e2, x1 * e2); e.y = cvt_pk_bf16(x2 * e2, x3 * e2); *(v2u*)(sb + T_XE + l * 80 + p4 * 2) = e;
;               *(v2u*)(sb + T_XS + l * 64 + p4 * 2) = R.Xr; *(v2u*)(sb + T_ZS + l * 64 + p4 * 2) = R.Zr;
;               if (w == 0) acP[lane] = R.aclane; }
;             BAR_LDS();
;             if (ci + 2 < nchunks) load_chunk(ci + 2, R);
;             bf16x8 cf[4];
; #pragma unroll
;             for (int k = 0; k < 4; ++k) cf[k] = *(const bf16x8*)(sb + T_CS + (lt * 16 + fr) * 272 + (k * 32 + fq * 8) * 2);
;             f32x4 yo = {0.f, 0.f, 0.f, 0.f};
; #pragma unroll
;             for (int k = 0; k < 4; ++k) { const bf16x8 bb = *(const bf16x8*)((const unsigned char*)StR + (pt * 16 + fr) * 272 + (k * 32 + fq * 8) * 2); yo = mfma16(cf[k], bb, yo); }
; { const f32x4 a4 = *(const f32x4*)(acP + lt * 16 + fq * 4);
; #pragma unroll
;               for (int j = 0; j < 4; ++j) yo[j] *= __expf(a4[j]); }
;             const float acl_fr = acP[lt * 16 + fr]; const int lrow = lt * 16 + fr;
; #pragma unroll
;             for (int t = 0; t < 2; ++t) {
;                 if (2 * t <= lt) {
;                     v2u xb0, xb1;
;                     { const unsigned a0 = lds0 + par * T_BUF + T_XD + (32 * t + 4 * fq + tq) * 80 + (pt * 16 + 4 * tp) * 2, a1 = a0 + 16 * 80; TR_ISSUE(xb0, a0); TR_ISSUE(xb1, a1); }
;                     float m[8];
	v_mul_f32_e32 v121, 0xbfb8aa3b, v113
	v_mul_f32_e32 v122, 0xbfb8aa3b, v114
	ds_write_b128 v213, v[156:159]
	v_mul_f32_e32 v123, 0xbfb8aa3b, v115
	ds_write_b128 v213, v[160:163] offset:8192
	v_exp_f32_e32 v120, v120
	ds_write_b128 v213, v[148:151] offset:16384
	v_exp_f32_e32 v121, v121
	ds_write_b128 v213, v[152:155] offset:24576
	v_exp_f32_e32 v122, v122
	v_exp_f32_e32 v123, v123
	v_sub_f32_e32 v200, v169, v168
	v_add_f32_e32 v120, 1.0, v120
	v_mul_f32_e32 v200, 0x3fb8aa3b, v200
	v_add_f32_e32 v121, 1.0, v121
	v_exp_f32_e32 v200, v200
	v_add_f32_e32 v122, 1.0, v122
	v_add_f32_e32 v123, 1.0, v123
	v_lshlrev_b32_e32 v196, 16, v164
	v_rcp_f32_e32 v120, v120
	v_and_b32_e32 v197, 0xffff0000, v164
	v_rcp_f32_e32 v121, v121
	v_lshlrev_b32_e32 v198, 16, v165
	v_rcp_f32_e32 v122, v122
	v_and_b32_e32 v199, 0xffff0000, v165
	v_rcp_f32_e32 v123, v123
	v_mul_f32_e32 v112, v120, v112
	v_mul_f32_e32 v196, v196, v118
	v_mul_f32_e32 v113, v121, v113
	v_mul_f32_e32 v197, v197, v118
	v_mul_f32_e32 v114, v122, v114
	v_mul_f32_e32 v198, v198, v118
	v_mul_f32_e32 v115, v123, v115
	v_lshlrev_b32_e32 v120, 16, v124
	v_mul_f32_e32 v199, v199, v118
	v_and_b32_e32 v121, 0xffff0000, v124
	v_cvt_pk_bf16_f32 v202, v196, v197
	v_lshlrev_b32_e32 v122, 16, v125
	v_cvt_pk_bf16_f32 v203, v198, v199
	v_and_b32_e32 v123, 0xffff0000, v125
	ds_write_b64 v215, v[202:203] offset:32768
	v_sub_f32_e32 v184, v194, v96
	v_sub_f32_e32 v185, v194, v97
	v_mul_f32_e32 v196, v196, v200
	v_sub_f32_e32 v186, v194, v98
	v_mul_f32_e32 v197, v197, v200
	v_sub_f32_e32 v187, v194, v99
	v_mul_f32_e32 v198, v198, v200
	v_exp_f32_e32 v184, v184
	v_exp_f32_e32 v185, v185
	v_mul_f32_e32 v199, v199, v200
	v_exp_f32_e32 v186, v186
	v_cvt_pk_bf16_f32 v192, v196, v197
	v_exp_f32_e32 v187, v187
	v_cvt_pk_bf16_f32 v193, v198, v199
	v_mul_f32_e32 v184, v48, v184
	ds_write_b64 v215, v[192:193] offset:37888
	v_mul_f32_e32 v185, v49, v185
	v_mul_f32_e32 v186, v50, v186
	ds_write_b64 v217, v[164:165] offset:43008
	v_mul_f32_e32 v187, v51, v187
	ds_write_b64 v217, v[166:167] offset:47616
	v_cndmask_b32_e64 v184, 0, v184, s[14:15]
	v_mul_f32_e32 v201, 0x3fb8aa3b, v168
	v_cndmask_b32_e64 v185, 0, v185, s[16:17]
	v_cndmask_b32_e64 v186, 0, v186, s[22:23]
	ds_write_b32 v218, v201 offset:256
	v_cndmask_b32_e64 v187, 0, v187, s[34:35]
	v_mul_f32_e32 v174, 0x3fb8aa3b, v169
	v_cvt_pk_bf16_f32 v128, v184, v185
	v_exp_f32_e32 v174, v174
	v_cvt_pk_bf16_f32 v129, v186, v187
	v_mov_b32_e32 v130, 0
	v_mov_b32_e32 v131, 0
	s_nop 1
	v_mfma_f32_16x16x32_bf16 v[24:27], v[56:59], v[128:131], v[24:27]
	s_mul_i32 s65, s56, 0x2000
	s_add_u32 s65, s65, 0x304f1000
	s_add_u32 s48, s0, s65
	s_addc_u32 s49, s1, 0
	s_nop 3
	v_fma_f32 v184, s61, v120, v24
	v_fma_f32 v185, s61, v121, v25
	v_fma_f32 v186, s61, v122, v26
	v_fma_f32 v187, s61, v123, v27
	v_mul_f32_e32 v184, v184, v112
	v_mul_f32_e32 v185, v185, v113
	v_mul_f32_e32 v186, v186, v114
	v_mul_f32_e32 v187, v187, v115
	v_cvt_pk_bf16_f32 v170, v184, v185
	v_cvt_pk_bf16_f32 v171, v186, v187
	global_store_dwordx2 v210, v[170:171], s[48:49]
	s_add_u32 s65, s54, 1
	s_sub_u32 s65, s65, s60
	s_lshl_b32 s65, s65, 6
	s_add_u32 s56, s65, s20
	s_waitcnt lgkmcnt(0)
	s_barrier
	s_add_u32 s54, s54, 1
	s_cmp_ge_u32 s54, s39
	s_cbranch_scc1 .Lssd_done
	ds_read_b128 v[28:31], v223
	ds_read_b128 v[32:35], v224
	ds_read_b128 v[40:43], v225
	ds_read_b128 v[44:47], v226
	ds_read_b128 v[48:51], v227 offset:8192
	ds_read_b128 v[52:55], v228 offset:8192
	ds_read_b128 v[56:59], v229 offset:8192
	ds_read_b128 v[60:63], v230 offset:8192
	ds_read_b32 v194, v231 offset:256
	ds_read_b64_tr_b16 v[96:97], v246 offset:16384
	ds_read_b64_tr_b16 v[98:99], v246 offset:20480
	ds_read_b64_tr_b16 v[100:101], v246 offset:24576
	ds_read_b64_tr_b16 v[102:103], v246 offset:28672
	ds_read_b64_tr_b16 v[104:105], v247 offset:16384
	ds_read_b64_tr_b16 v[106:107], v247 offset:20480
	s_waitcnt lgkmcnt(11)
	ds_read_b64_tr_b16 v[108:109], v247 offset:24576
	ds_read_b64_tr_b16 v[110:111], v247 offset:28672
	ds_read_b64_tr_b16 v[112:113], v243 offset:37888
	ds_read_b64_tr_b16 v[114:115], v243 offset:39168
	s_waitcnt lgkmcnt(11)
	ds_read_b64_tr_b16 v[124:125], v243 offset:37920
	ds_read_b64_tr_b16 v[126:127], v243 offset:39200
	ds_read_b64_tr_b16 v[120:121], v243 offset:40448
	ds_read_b64_tr_b16 v[122:123], v243 offset:41728
	global_load_dwordx4 v[156:159], v204, s[40:41] offset:2048
	s_waitcnt lgkmcnt(11)
	ds_read_b64_tr_b16 v[128:129], v243 offset:40480
	ds_read_b64_tr_b16 v[130:131], v243 offset:41760
	global_load_dwordx4 v[160:163], v205, s[40:41] offset:2048
	ds_read_b128 v[64:67], v223 offset:16384
	ds_read_b128 v[68:71], v224 offset:16384
	s_waitcnt lgkmcnt(11)
	ds_read_b128 v[72:75], v225 offset:16384
	global_load_dwordx4 v[148:151], v204, s[40:41]
	ds_read_b128 v[76:79], v226 offset:16384
	v_mfma_f32_16x16x32_bf16 v[24:27], v[48:51], v[28:31], 0
	global_load_dwordx4 v[152:155], v205, s[40:41]
	v_mfma_f32_16x16x32_bf16 v[24:27], v[52:55], v[32:35], v[24:27]
	v_mfma_f32_16x16x32_bf16 v[24:27], v[56:59], v[40:43], v[24:27]
	v_mfma_f32_16x16x32_bf16 v[24:27], v[60:63], v[44:47], v[24:27]
	global_load_dwordx2 v[164:165], v206, s[40:41]
	ds_read_b64_tr_b16 v[56:57], v234 offset:32768
	ds_read_b64_tr_b16 v[58:59], v234 offset:34048
	global_load_dwordx2 v[166:167], v207, s[42:43] nt
	v_mul_f32_e32 v8, v8, v174
	v_mul_f32_e32 v9, v9, v174
	v_mul_f32_e32 v10, v10, v174
	global_load_dword v118, v208, s[44:45]
	v_mul_f32_e32 v11, v11, v174
	v_mul_f32_e32 v12, v12, v174
	v_mul_f32_e32 v13, v13, v174
	global_load_dword v168, v208, s[46:47]
	v_mul_f32_e32 v14, v14, v174
	v_mul_f32_e32 v15, v15, v174
	global_load_dword v169, v209, s[46:47]
	v_mul_f32_e32 v16, v16, v174
	v_mul_f32_e32 v17, v17, v174
	v_mul_f32_e32 v18, v18, v174
	s_add_u32 s66, s54, 3
	s_cmp_lt_u32 s66, s39
	s_cselect_b32 s74, 0xc0000, 0
	s_cselect_b32 s75, 0x280000, 0
	s_cselect_b32 s76, 0x4000, 0
	s_add_u32 s40, s40, s74
	s_addc_u32 s41, s41, 0
	s_add_u32 s42, s42, s75
	s_addc_u32 s43, s43, 0
	s_add_u32 s44, s44, s76
	s_addc_u32 s45, s45, 0
	s_add_u32 s46, s46, s76
	s_addc_u32 s47, s47, 0
	v_mul_f32_e32 v19, v19, v174
	v_mul_f32_e32 v20, v20, v174
	v_mul_f32_e32 v21, v21, v174
	v_mul_f32_e32 v22, v22, v174
	v_mul_f32_e32 v23, v23, v174
	s_waitcnt lgkmcnt(12)
; __device__ __forceinline__ void phase_ssd(const Params& P, int seg, unsigned char* smem) {
;     ...
;         auto step = [&](int ci, Pre& R, const int par) {
;             const int row0 = chunk_row0(ci); unsigned char* sb = smem + par * T_BUF; float* acP = acS + par * 64;
;             const bf16* StR = StS + par * (T_STSZ / 2); bf16* StW = StS + (par ^ 1) * (T_STSZ / 2);
;             const float dec = __expf(R.alast);
;             { const float e2 = __expf(R.alast - R.acl);
; #pragma unroll
;               for (int i = 0; i < 2; ++i) { const int q = tid + 512 * i, l = q >> 4, c8 = q & 15; *(v4u*)(sb + T_CS + l * 272 + c8 * 16) = R.Cr[i]; *(v4u*)(sb + T_BS + l * 272 + c8 * 16) = R.Br[i]; }
;               const int l = tid >> 3, p4 = (tid & 7) * 4;
;               const float x0 = bflo(R.Xr.x) * R.dtl, x1 = bfhi(R.Xr.x) * R.dtl, x2 = bflo(R.Xr.y) * R.dtl, x3 = bfhi(R.Xr.y) * R.dtl;
;               v2u d; d.x = cvt_pk_bf16(x0, x1); d.y = cvt_pk_bf16(x2, x3); *(v2u*)(sb + T_XD + l * 80 + p4 * 2) = d;
;               v2u e; e.x = cvt_pk_bf16(x0 * e2, x1 * e2); e.y = cvt_pk_bf16(x2 * e2, x3 * e2); *(v2u*)(sb + T_XE + l * 80 + p4 * 2) = e;
;               *(v2u*)(sb + T_XS + l * 64 + p4 * 2) = R.Xr; *(v2u*)(sb + T_ZS + l * 64 + p4 * 2) = R.Zr;
;               if (w == 0) acP[lane] = R.aclane; }
;             BAR_LDS();
;             if (ci + 2 < nchunks) load_chunk(ci + 2, R);
;             bf16x8 cf[4];
; #pragma unroll
;             for (int k = 0; k < 4; ++k) cf[k] = *(const bf16x8*)(sb + T_CS + (lt * 16 + fr) * 272 + (k * 32 + fq * 8) * 2);
;             f32x4 yo = {0.f, 0.f, 0.f, 0.f};
; #pragma unroll
;             for (int k = 0; k < 4; ++k) { const bf16x8 bb = *(const bf16x8*)((const unsigned char*)StR + (pt * 16 + fr) * 272 + (k * 32 + fq * 8) * 2); yo = mfma16(cf[k], bb, yo); }
; { const f32x4 a4 = *(const f32x4*)(acP + lt * 16 + fq * 4);
; #pragma unroll
;               for (int j = 0; j < 4; ++j) yo[j] *= __expf(a4[j]); }
;             const float acl_fr = acP[lt * 16 + fr]; const int lrow = lt * 16 + fr;
; #pragma unroll
;             for (int t = 0; t < 2; ++t) {
;                 if (2 * t <= lt) {
;                     v2u xb0, xb1;
;                     { const unsigned a0 = lds0 + par * T_BUF + T_XD + (32 * t + 4 * fq + tq) * 80 + (pt * 16 + 4 * tp) * 2, a1 = a0 + 16 * 80; TR_ISSUE(xb0, a0); TR_ISSUE(xb1, a1); }
;                     float m[8];
	v_mfma_f32_16x16x32_bf16 v[8:11], v[96:99], v[112:115], v[8:11]
	s_waitcnt lgkmcnt(10)
	v_mfma_f32_16x16x32_bf16 v[12:15], v[96:99], v[124:127], v[12:15]
	v_mfma_f32_16x16x32_bf16 v[16:19], v[104:107], v[112:115], v[16:19]
	v_mfma_f32_16x16x32_bf16 v[20:23], v[104:107], v[124:127], v[20:23]
	s_waitcnt lgkmcnt(8)
	v_mfma_f32_16x16x32_bf16 v[8:11], v[100:103], v[120:123], v[8:11]
	s_waitcnt lgkmcnt(6)
	v_mfma_f32_16x16x32_bf16 v[12:15], v[100:103], v[128:131], v[12:15]
	v_mfma_f32_16x16x32_bf16 v[16:19], v[108:111], v[120:123], v[16:19]
	v_mfma_f32_16x16x32_bf16 v[20:23], v[108:111], v[128:131], v[20:23]
	ds_read_b128 v[96:99], v232 offset:256
	ds_read_b64 v[124:125], v236 offset:43008
	ds_read_b64 v[126:127], v236 offset:47616
	s_waitcnt lgkmcnt(8)
	v_mfma_f32_16x16x32_bf16 v[48:51], v[64:67], v[28:31], 0
	s_waitcnt lgkmcnt(7)
	v_mfma_f32_16x16x32_bf16 v[48:51], v[68:71], v[32:35], v[48:51]
	s_waitcnt lgkmcnt(6)
	v_mfma_f32_16x16x32_bf16 v[48:51], v[72:75], v[40:43], v[48:51]
	s_waitcnt lgkmcnt(5)
	v_mfma_f32_16x16x32_bf16 v[48:51], v[76:79], v[44:47], v[48:51]
	v_exp_f32_e32 v195, v194
	s_nop 0
	v_mul_f32_e32 v24, v24, v195
	v_mul_f32_e32 v25, v25, v195
	v_mul_f32_e32 v26, v26, v195
	v_mul_f32_e32 v27, v27, v195
	v_cvt_pk_bf16_f32 v184, v8, v9
	v_cvt_pk_bf16_f32 v185, v10, v11
	v_cvt_pk_bf16_f32 v186, v12, v13
	v_cvt_pk_bf16_f32 v187, v14, v15
	v_cvt_pk_bf16_f32 v188, v16, v17
	v_cvt_pk_bf16_f32 v189, v18, v19
	v_cvt_pk_bf16_f32 v190, v20, v21
	v_cvt_pk_bf16_f32 v191, v22, v23
	ds_write_b64 v248, v[184:185]
	ds_write_b64 v248, v[186:187] offset:4096
	ds_write_b64 v249, v[188:189]
	ds_write_b64 v249, v[190:191] offset:4096
	s_waitcnt lgkmcnt(4)
	v_lshlrev_b32_e32 v112, 16, v126
	v_and_b32_e32 v113, 0xffff0000, v126
	v_lshlrev_b32_e32 v114, 16, v127
	v_and_b32_e32 v115, 0xffff0000, v127
	v_mul_f32_e32 v120, 0xbfb8aa3b, v112
	s_waitcnt vmcnt(10)
	v_mul_f32_e32 v121, 0xbfb8aa3b, v113
	v_mul_f32_e32 v122, 0xbfb8aa3b, v114
	ds_write_b128 v212, v[140:143]
	v_mul_f32_e32 v123, 0xbfb8aa3b, v115
	ds_write_b128 v212, v[144:147] offset:8192
	v_exp_f32_e32 v120, v120
	ds_write_b128 v212, v[132:135] offset:16384
	v_exp_f32_e32 v121, v121
	ds_write_b128 v212, v[136:139] offset:24576
	v_exp_f32_e32 v122, v122
	v_exp_f32_e32 v123, v123
	v_sub_f32_e32 v200, v117, v116
	v_add_f32_e32 v120, 1.0, v120
	v_mul_f32_e32 v200, 0x3fb8aa3b, v200
	v_add_f32_e32 v121, 1.0, v121
	v_exp_f32_e32 v200, v200
	v_add_f32_e32 v122, 1.0, v122
	v_add_f32_e32 v123, 1.0, v123
	v_lshlrev_b32_e32 v196, 16, v4
	v_rcp_f32_e32 v120, v120
	v_and_b32_e32 v197, 0xffff0000, v4
	v_rcp_f32_e32 v121, v121
	v_lshlrev_b32_e32 v198, 16, v5
	v_rcp_f32_e32 v122, v122
	v_and_b32_e32 v199, 0xffff0000, v5
	v_rcp_f32_e32 v123, v123
	v_mul_f32_e32 v112, v120, v112
	v_mul_f32_e32 v196, v196, v6
	v_mul_f32_e32 v113, v121, v113
	v_mul_f32_e32 v197, v197, v6
	v_mul_f32_e32 v114, v122, v114
	v_mul_f32_e32 v198, v198, v6
	v_mul_f32_e32 v115, v123, v115
	v_lshlrev_b32_e32 v120, 16, v124
	v_mul_f32_e32 v199, v199, v6
	v_and_b32_e32 v121, 0xffff0000, v124
	v_cvt_pk_bf16_f32 v202, v196, v197
	v_lshlrev_b32_e32 v122, 16, v125
	v_cvt_pk_bf16_f32 v203, v198, v199
	v_and_b32_e32 v123, 0xffff0000, v125
	ds_write_b64 v214, v[202:203] offset:32768
	v_sub_f32_e32 v184, v194, v96
	v_sub_f32_e32 v185, v194, v97
	v_mul_f32_e32 v196, v196, v200
	v_sub_f32_e32 v186, v194, v98
	v_mul_f32_e32 v197, v197, v200
	v_sub_f32_e32 v187, v194, v99
	v_mul_f32_e32 v198, v198, v200
	v_exp_f32_e32 v184, v184
	v_exp_f32_e32 v185, v185
	v_mul_f32_e32 v199, v199, v200
	v_exp_f32_e32 v186, v186
	v_cvt_pk_bf16_f32 v192, v196, v197
	v_exp_f32_e32 v187, v187
	v_cvt_pk_bf16_f32 v193, v198, v199
	v_mul_f32_e32 v184, v48, v184
	ds_write_b64 v214, v[192:193] offset:37888
	v_mul_f32_e32 v185, v49, v185
	v_mul_f32_e32 v186, v50, v186
	ds_write_b64 v216, v[4:5] offset:43008
	v_mul_f32_e32 v187, v51, v187
	ds_write_b64 v216, v[36:37] offset:47616
	v_cndmask_b32_e64 v184, 0, v184, s[14:15]
	v_mul_f32_e32 v201, 0x3fb8aa3b, v116
	v_cndmask_b32_e64 v185, 0, v185, s[16:17]
	v_cndmask_b32_e64 v186, 0, v186, s[22:23]
	ds_write_b32 v218, v201
	v_cndmask_b32_e64 v187, 0, v187, s[34:35]
	v_mul_f32_e32 v174, 0x3fb8aa3b, v117
	v_cvt_pk_bf16_f32 v128, v184, v185
	v_exp_f32_e32 v174, v174
	v_cvt_pk_bf16_f32 v129, v186, v187
	v_mov_b32_e32 v130, 0
	v_mov_b32_e32 v131, 0
	s_nop 1
	v_mfma_f32_16x16x32_bf16 v[24:27], v[56:59], v[128:131], v[24:27]
	s_mul_i32 s65, s56, 0x2000
	s_add_u32 s65, s65, 0x304f1000
	s_add_u32 s48, s0, s65
	s_addc_u32 s49, s1, 0
	s_nop 3
	v_fma_f32 v184, s61, v120, v24
	v_fma_f32 v185, s61, v121, v25
	v_fma_f32 v186, s61, v122, v26
	v_fma_f32 v187, s61, v123, v27
	v_mul_f32_e32 v184, v184, v112
	v_mul_f32_e32 v185, v185, v113
	v_mul_f32_e32 v186, v186, v114
	v_mul_f32_e32 v187, v187, v115
	v_cvt_pk_bf16_f32 v170, v184, v185
	v_cvt_pk_bf16_f32 v171, v186, v187
	global_store_dwordx2 v210, v[170:171], s[48:49]
	s_add_u32 s65, s54, 1
	s_sub_u32 s65, s65, s60
	s_lshl_b32 s65, s65, 6
	s_add_u32 s56, s65, s20
	s_waitcnt lgkmcnt(0)
	s_barrier
	s_add_u32 s54, s54, 1
	s_cmp_lt_u32 s54, s39
	s_cbranch_scc1 .Lssd_loop0
	s_branch .Lssd_done
; __device__ __forceinline__ void phase_ssd(const Params& P, int seg, unsigned char* smem) {
;     ...
;         auto step = [&](int ci, Pre& R, const int par) {
;             const int row0 = chunk_row0(ci); unsigned char* sb = smem + par * T_BUF; float* acP = acS + par * 64;
;             const bf16* StR = StS + par * (T_STSZ / 2); bf16* StW = StS + (par ^ 1) * (T_STSZ / 2);
;             const float dec = __expf(R.alast);
;             { const float e2 = __expf(R.alast - R.acl);
; #pragma unroll
;               for (int i = 0; i < 2; ++i) { const int q = tid + 512 * i, l = q >> 4, c8 = q & 15; *(v4u*)(sb + T_CS + l * 272 + c8 * 16) = R.Cr[i]; *(v4u*)(sb + T_BS + l * 272 + c8 * 16) = R.Br[i]; }
;               const int l = tid >> 3, p4 = (tid & 7) * 4;
;               const float x0 = bflo(R.Xr.x) * R.dtl, x1 = bfhi(R.Xr.x) * R.dtl, x2 = bflo(R.Xr.y) * R.dtl, x3 = bfhi(R.Xr.y) * R.dtl;
;               v2u d; d.x = cvt_pk_bf16(x0, x1); d.y = cvt_pk_bf16(x2, x3); *(v2u*)(sb + T_XD + l * 80 + p4 * 2) = d;
;               v2u e; e.x = cvt_pk_bf16(x0 * e2, x1 * e2); e.y = cvt_pk_bf16(x2 * e2, x3 * e2); *(v2u*)(sb + T_XE + l * 80 + p4 * 2) = e;
;               *(v2u*)(sb + T_XS + l * 64 + p4 * 2) = R.Xr; *(v2u*)(sb + T_ZS + l * 64 + p4 * 2) = R.Zr;
;               if (w == 0) acP[lane] = R.aclane; }
;             BAR_LDS();
;             if (ci + 2 < nchunks) load_chunk(ci + 2, R);
;             bf16x8 cf[4];
; #pragma unroll
;             for (int k = 0; k < 4; ++k) cf[k] = *(const bf16x8*)(sb + T_CS + (lt * 16 + fr) * 272 + (k * 32 + fq * 8) * 2);
;             f32x4 yo = {0.f, 0.f, 0.f, 0.f};
; #pragma unroll
;             for (int k = 0; k < 4; ++k) { const bf16x8 bb = *(const bf16x8*)((const unsigned char*)StR + (pt * 16 + fr) * 272 + (k * 32 + fq * 8) * 2); yo = mfma16(cf[k], bb, yo); }
; { const f32x4 a4 = *(const f32x4*)(acP + lt * 16 + fq * 4);
; #pragma unroll
;               for (int j = 0; j < 4; ++j) yo[j] *= __expf(a4[j]); }
;             const float acl_fr = acP[lt * 16 + fr]; const int lrow = lt * 16 + fr;
; #pragma unroll
;             for (int t = 0; t < 2; ++t) {
;                 if (2 * t <= lt) {
;                     v2u xb0, xb1;
;                     { const unsigned a0 = lds0 + par * T_BUF + T_XD + (32 * t + 4 * fq + tq) * 80 + (pt * 16 + 4 * tp) * 2, a1 = a0 + 16 * 80; TR_ISSUE(xb0, a0); TR_ISSUE(xb1, a1); }
;                     float m[8];
.Lssd_loop1:
	ds_read_b128 v[28:31], v219 offset:4096
	ds_read_b128 v[32:35], v220 offset:4096
	ds_read_b128 v[40:43], v221 offset:4096
	ds_read_b128 v[44:47], v222 offset:4096
	ds_read_b128 v[48:51], v227
	ds_read_b128 v[52:55], v228
	ds_read_b128 v[56:59], v229
	ds_read_b128 v[60:63], v230
	ds_read_b32 v194, v231 offset:64
	ds_read_b64_tr_b16 v[96:97], v244 offset:16384
	ds_read_b64_tr_b16 v[98:99], v244 offset:20480
	ds_read_b64_tr_b16 v[100:101], v244 offset:24576
	ds_read_b64_tr_b16 v[102:103], v244 offset:28672
	ds_read_b64_tr_b16 v[104:105], v245 offset:16384
	ds_read_b64_tr_b16 v[106:107], v245 offset:20480
	s_waitcnt lgkmcnt(11)
	ds_read_b64_tr_b16 v[108:109], v245 offset:24576
	ds_read_b64_tr_b16 v[110:111], v245 offset:28672
	ds_read_b64_tr_b16 v[112:113], v237 offset:37888
	ds_read_b64_tr_b16 v[114:115], v237 offset:39168
	s_waitcnt lgkmcnt(11)
	ds_read_b64_tr_b16 v[124:125], v237 offset:37920
	ds_read_b64_tr_b16 v[126:127], v237 offset:39200
	ds_read_b64_tr_b16 v[120:121], v237 offset:40448
	ds_read_b64_tr_b16 v[122:123], v237 offset:41728
	s_waitcnt lgkmcnt(11)
	ds_read_b64_tr_b16 v[128:129], v237 offset:40480
	ds_read_b64_tr_b16 v[130:131], v237 offset:41760
	ds_read_b128 v[64:67], v219 offset:16384
	ds_read_b128 v[68:71], v220 offset:16384
	global_load_dwordx4 v[140:143], v204, s[40:41] offset:2048
	s_waitcnt lgkmcnt(11)
	ds_read_b128 v[72:75], v221 offset:16384
	ds_read_b128 v[76:79], v222 offset:16384
	global_load_dwordx4 v[144:147], v205, s[40:41] offset:2048
	ds_read_b128 v[80:83], v219 offset:20480
	ds_read_b128 v[84:87], v220 offset:20480
	s_waitcnt lgkmcnt(11)
	ds_read_b128 v[88:91], v221 offset:20480
	global_load_dwordx4 v[132:135], v204, s[40:41]
	ds_read_b128 v[92:95], v222 offset:20480
	v_mfma_f32_16x16x32_bf16 v[24:27], v[48:51], v[28:31], 0
	v_mfma_f32_16x16x32_bf16 v[24:27], v[52:55], v[32:35], v[24:27]
	global_load_dwordx4 v[136:139], v205, s[40:41]
	v_mfma_f32_16x16x32_bf16 v[24:27], v[56:59], v[40:43], v[24:27]
	v_mfma_f32_16x16x32_bf16 v[24:27], v[60:63], v[44:47], v[24:27]
	ds_read_b64_tr_b16 v[56:57], v233 offset:32768
	global_load_dwordx2 v[4:5], v206, s[40:41]
	ds_read_b64_tr_b16 v[58:59], v233 offset:34048
	v_mul_f32_e32 v8, v8, v174
	v_mul_f32_e32 v9, v9, v174
	global_load_dwordx2 v[36:37], v207, s[42:43] nt
	v_mul_f32_e32 v10, v10, v174
	v_mul_f32_e32 v11, v11, v174
	v_mul_f32_e32 v12, v12, v174
	global_load_dword v6, v208, s[44:45]
	v_mul_f32_e32 v13, v13, v174
	v_mul_f32_e32 v14, v14, v174
	v_mul_f32_e32 v15, v15, v174
	global_load_dword v116, v208, s[46:47]
	v_mul_f32_e32 v16, v16, v174
	v_mul_f32_e32 v17, v17, v174
	v_mul_f32_e32 v18, v18, v174
	global_load_dword v117, v209, s[46:47]
	v_mul_f32_e32 v19, v19, v174
	v_mul_f32_e32 v20, v20, v174
	v_mul_f32_e32 v21, v21, v174
	s_add_u32 s66, s54, 3
	s_cmp_lt_u32 s66, s39
	s_cselect_b32 s74, 0xc0000, 0
	s_cselect_b32 s75, 0x280000, 0
	s_cselect_b32 s76, 0x4000, 0
	s_add_u32 s40, s40, s74
	s_addc_u32 s41, s41, 0
	s_add_u32 s42, s42, s75
	s_addc_u32 s43, s43, 0
	s_add_u32 s44, s44, s76
	s_addc_u32 s45, s45, 0
	s_add_u32 s46, s46, s76
	s_addc_u32 s47, s47, 0
	v_mul_f32_e32 v22, v22, v174
	v_mul_f32_e32 v23, v23, v174
	v_mfma_f32_16x16x32_bf16 v[8:11], v[96:99], v[112:115], v[8:11]
	s_waitcnt lgkmcnt(14)
	v_mfma_f32_16x16x32_bf16 v[12:15], v[96:99], v[124:127], v[12:15]
	v_mfma_f32_16x16x32_bf16 v[16:19], v[104:107], v[112:115], v[16:19]
	v_mfma_f32_16x16x32_bf16 v[20:23], v[104:107], v[124:127], v[20:23]
	s_waitcnt lgkmcnt(12)
	v_mfma_f32_16x16x32_bf16 v[8:11], v[100:103], v[120:123], v[8:11]
	s_waitcnt lgkmcnt(10)
	v_mfma_f32_16x16x32_bf16 v[12:15], v[100:103], v[128:131], v[12:15]
	v_mfma_f32_16x16x32_bf16 v[16:19], v[108:111], v[120:123], v[16:19]
	v_mfma_f32_16x16x32_bf16 v[20:23], v[108:111], v[128:131], v[20:23]
	ds_read_b128 v[96:99], v232
	ds_read_b128 v[100:103], v232 offset:64
	ds_read_b64 v[124:125], v235 offset:44160
	ds_read_b64 v[126:127], v235 offset:48768
	s_waitcnt lgkmcnt(13)
	v_mfma_f32_16x16x32_bf16 v[48:51], v[64:67], v[28:31], 0
	s_waitcnt lgkmcnt(9)
	v_mfma_f32_16x16x32_bf16 v[52:55], v[80:83], v[28:31], 0
	v_mfma_f32_16x16x32_bf16 v[48:51], v[68:71], v[32:35], v[48:51]
	s_waitcnt lgkmcnt(8)
	v_mfma_f32_16x16x32_bf16 v[52:55], v[84:87], v[32:35], v[52:55]
	v_mfma_f32_16x16x32_bf16 v[48:51], v[72:75], v[40:43], v[48:51]
	s_waitcnt lgkmcnt(7)
	v_mfma_f32_16x16x32_bf16 v[52:55], v[88:91], v[40:43], v[52:55]
	v_mfma_f32_16x16x32_bf16 v[48:51], v[76:79], v[44:47], v[48:51]
	s_waitcnt lgkmcnt(6)
	v_mfma_f32_16x16x32_bf16 v[52:55], v[92:95], v[44:47], v[52:55]
	v_exp_f32_e32 v195, v194
	s_nop 0
	v_mul_f32_e32 v24, v24, v195
	v_mul_f32_e32 v25, v25, v195
	v_mul_f32_e32 v26, v26, v195
	v_mul_f32_e32 v27, v27, v195
	v_cvt_pk_bf16_f32 v184, v8, v9
	v_cvt_pk_bf16_f32 v185, v10, v11
	v_cvt_pk_bf16_f32 v186, v12, v13
	v_cvt_pk_bf16_f32 v187, v14, v15
	v_cvt_pk_bf16_f32 v188, v16, v17
	v_cvt_pk_bf16_f32 v189, v18, v19
	v_cvt_pk_bf16_f32 v190, v20, v21
	v_cvt_pk_bf16_f32 v191, v22, v23
	ds_write_b64 v248, v[184:185] offset:8192
	ds_write_b64 v248, v[186:187] offset:12288
	ds_write_b64 v249, v[188:189] offset:8192
	ds_write_b64 v249, v[190:191] offset:12288
	s_waitcnt lgkmcnt(4)
	v_lshlrev_b32_e32 v112, 16, v126
	v_and_b32_e32 v113, 0xffff0000, v126
	v_lshlrev_b32_e32 v114, 16, v127
	v_and_b32_e32 v115, 0xffff0000, v127
	v_mul_f32_e32 v120, 0xbfb8aa3b, v112
	v_mul_f32_e32 v121, 0xbfb8aa3b, v113
	v_mul_f32_e32 v122, 0xbfb8aa3b, v114
	v_mul_f32_e32 v123, 0xbfb8aa3b, v115
	v_exp_f32_e32 v120, v120
	v_exp_f32_e32 v121, v121
	v_exp_f32_e32 v122, v122
	s_waitcnt vmcnt(10)
; __device__ __forceinline__ void phase_ssd(const Params& P, int seg, unsigned char* smem) {
;     ...
;         auto step = [&](int ci, Pre& R, const int par) {
;             const int row0 = chunk_row0(ci); unsigned char* sb = smem + par * T_BUF; float* acP = acS + par * 64;
;             const bf16* StR = StS + par * (T_STSZ / 2); bf16* StW = StS + (par ^ 1) * (T_STSZ / 2);
;             const float dec = __expf(R.alast);
;             { const float e2 = __expf(R.alast - R.acl);
; #pragma unroll
;               for (int i = 0; i < 2; ++i) { const int q = tid + 512 * i, l = q >> 4, c8 = q & 15; *(v4u*)(sb + T_CS + l * 272 + c8 * 16) = R.Cr[i]; *(v4u*)(sb + T_BS + l * 272 + c8 * 16) = R.Br[i]; }
;               const int l = tid >> 3, p4 = (tid & 7) * 4;
;               const float x0 = bflo(R.Xr.x) * R.dtl, x1 = bfhi(R.Xr.x) * R.dtl, x2 = bflo(R.Xr.y) * R.dtl, x3 = bfhi(R.Xr.y) * R.dtl;
;               v2u d; d.x = cvt_pk_bf16(x0, x1); d.y = cvt_pk_bf16(x2, x3); *(v2u*)(sb + T_XD + l * 80 + p4 * 2) = d;
;               v2u e; e.x = cvt_pk_bf16(x0 * e2, x1 * e2); e.y = cvt_pk_bf16(x2 * e2, x3 * e2); *(v2u*)(sb + T_XE + l * 80 + p4 * 2) = e;
;               *(v2u*)(sb + T_XS + l * 64 + p4 * 2) = R.Xr; *(v2u*)(sb + T_ZS + l * 64 + p4 * 2) = R.Zr;
;               if (w == 0) acP[lane] = R.aclane; }
;             BAR_LDS();
;             if (ci + 2 < nchunks) load_chunk(ci + 2, R);
;             bf16x8 cf[4];
; #pragma unroll
;             for (int k = 0; k < 4; ++k) cf[k] = *(const bf16x8*)(sb + T_CS + (lt * 16 + fr) * 272 + (k * 32 + fq * 8) * 2);
;             f32x4 yo = {0.f, 0.f, 0.f, 0.f};
; #pragma unroll
;             for (int k = 0; k < 4; ++k) { const bf16x8 bb = *(const bf16x8*)((const unsigned char*)StR + (pt * 16 + fr) * 272 + (k * 32 + fq * 8) * 2); yo = mfma16(cf[k], bb, yo); }
; { const f32x4 a4 = *(const f32x4*)(acP + lt * 16 + fq * 4);
; #pragma unroll
;               for (int j = 0; j < 4; ++j) yo[j] *= __expf(a4[j]); }
;             const float acl_fr = acP[lt * 16 + fr]; const int lrow = lt * 16 + fr;
; #pragma unroll
;             for (int t = 0; t < 2; ++t) {
;                 if (2 * t <= lt) {
;                     v2u xb0, xb1;
;                     { const unsigned a0 = lds0 + par * T_BUF + T_XD + (32 * t + 4 * fq + tq) * 80 + (pt * 16 + 4 * tp) * 2, a1 = a0 + 16 * 80; TR_ISSUE(xb0, a0); TR_ISSUE(xb1, a1); }
;                     float m[8];
	v_exp_f32_e32 v123, v123
	ds_write_b128 v213, v[156:159]
	v_add_f32_e32 v120, 1.0, v120
	v_add_f32_e32 v121, 1.0, v121
	ds_write_b128 v213, v[160:163] offset:8192
	v_add_f32_e32 v122, 1.0, v122
	ds_write_b128 v213, v[148:151] offset:16384
	v_add_f32_e32 v123, 1.0, v123
	v_rcp_f32_e32 v120, v120
	ds_write_b128 v213, v[152:155] offset:24576
	v_rcp_f32_e32 v121, v121
	v_sub_f32_e32 v200, v169, v168
	v_rcp_f32_e32 v122, v122
	v_rcp_f32_e32 v123, v123
	v_mul_f32_e32 v200, 0x3fb8aa3b, v200
	v_mul_f32_e32 v112, v120, v112
	v_exp_f32_e32 v200, v200
	v_mul_f32_e32 v113, v121, v113
	v_mul_f32_e32 v114, v122, v114
	v_lshlrev_b32_e32 v196, 16, v164
	v_mul_f32_e32 v115, v123, v115
	v_and_b32_e32 v197, 0xffff0000, v164
	v_lshlrev_b32_e32 v120, 16, v124
	v_and_b32_e32 v121, 0xffff0000, v124
	v_lshlrev_b32_e32 v198, 16, v165
	v_lshlrev_b32_e32 v122, 16, v125
	v_and_b32_e32 v199, 0xffff0000, v165
	v_and_b32_e32 v123, 0xffff0000, v125
	v_sub_f32_e32 v184, v194, v96
	v_mul_f32_e32 v196, v196, v118
	v_sub_f32_e32 v185, v194, v97
	v_mul_f32_e32 v197, v197, v118
	v_sub_f32_e32 v186, v194, v98
	v_sub_f32_e32 v187, v194, v99
	v_mul_f32_e32 v198, v198, v118
	v_exp_f32_e32 v184, v184
	v_mul_f32_e32 v199, v199, v118
	v_exp_f32_e32 v185, v185
	v_exp_f32_e32 v186, v186
	v_cvt_pk_bf16_f32 v202, v196, v197
	v_exp_f32_e32 v187, v187
	v_cvt_pk_bf16_f32 v203, v198, v199
	v_mul_f32_e32 v184, v48, v184
	v_mul_f32_e32 v185, v49, v185
	ds_write_b64 v215, v[202:203] offset:32768
	v_mul_f32_e32 v186, v50, v186
	v_mul_f32_e32 v196, v196, v200
	v_mul_f32_e32 v187, v51, v187
	v_sub_f32_e32 v188, v194, v100
	v_mul_f32_e32 v197, v197, v200
	v_sub_f32_e32 v189, v194, v101
	v_mul_f32_e32 v198, v198, v200
	v_sub_f32_e32 v190, v194, v102
	v_sub_f32_e32 v191, v194, v103
	v_mul_f32_e32 v199, v199, v200
	v_exp_f32_e32 v188, v188
	v_cvt_pk_bf16_f32 v192, v196, v197
	v_exp_f32_e32 v189, v189
	v_exp_f32_e32 v190, v190
	v_cvt_pk_bf16_f32 v193, v198, v199
	v_exp_f32_e32 v191, v191
	ds_write_b64 v215, v[192:193] offset:37888
	v_mul_f32_e32 v188, v52, v188
	v_mul_f32_e32 v189, v53, v189
	ds_write_b64 v217, v[164:165] offset:43008
	v_mul_f32_e32 v190, v54, v190
	ds_write_b64 v217, v[166:167] offset:47616
	v_mul_f32_e32 v191, v55, v191
	v_cndmask_b32_e64 v188, 0, v188, s[14:15]
	v_mul_f32_e32 v201, 0x3fb8aa3b, v168
	v_cndmask_b32_e64 v189, 0, v189, s[16:17]
	ds_write_b32 v218, v201 offset:256
	v_cndmask_b32_e64 v190, 0, v190, s[22:23]
	v_cndmask_b32_e64 v191, 0, v191, s[34:35]
	v_mul_f32_e32 v174, 0x3fb8aa3b, v169
	v_cvt_pk_bf16_f32 v128, v184, v185
	v_exp_f32_e32 v174, v174
	v_cvt_pk_bf16_f32 v129, v186, v187
	v_cvt_pk_bf16_f32 v130, v188, v189
	v_cvt_pk_bf16_f32 v131, v190, v191
	s_nop 1
	v_mfma_f32_16x16x32_bf16 v[24:27], v[56:59], v[128:131], v[24:27]
	s_mul_i32 s65, s56, 0x2000
	s_add_u32 s65, s65, 0x304f1000
	s_add_u32 s48, s0, s65
	s_addc_u32 s49, s1, 0
	s_nop 3
	v_fma_f32 v184, s61, v120, v24
	v_fma_f32 v185, s61, v121, v25
	v_fma_f32 v186, s61, v122, v26
	v_fma_f32 v187, s61, v123, v27
	v_mul_f32_e32 v184, v184, v112
	v_mul_f32_e32 v185, v185, v113
	v_mul_f32_e32 v186, v186, v114
	v_mul_f32_e32 v187, v187, v115
	v_cvt_pk_bf16_f32 v170, v184, v185
	v_cvt_pk_bf16_f32 v171, v186, v187
	global_store_dwordx2 v210, v[170:171], s[48:49]
	s_add_u32 s65, s54, 1
	s_sub_u32 s65, s65, s60
	s_lshl_b32 s65, s65, 6
	s_add_u32 s56, s65, s20
	s_waitcnt lgkmcnt(0)
	s_barrier
	s_add_u32 s54, s54, 1
	s_cmp_ge_u32 s54, s39
	s_cbranch_scc1 .Lssd_done
	ds_read_b128 v[28:31], v223 offset:4096
	ds_read_b128 v[32:35], v224 offset:4096
	ds_read_b128 v[40:43], v225 offset:4096
	ds_read_b128 v[44:47], v226 offset:4096
	ds_read_b128 v[48:51], v227 offset:8192
	ds_read_b128 v[52:55], v228 offset:8192
	ds_read_b128 v[56:59], v229 offset:8192
	ds_read_b128 v[60:63], v230 offset:8192
	ds_read_b32 v194, v231 offset:320
	ds_read_b64_tr_b16 v[96:97], v246 offset:16384
	ds_read_b64_tr_b16 v[98:99], v246 offset:20480
	ds_read_b64_tr_b16 v[100:101], v246 offset:24576
	ds_read_b64_tr_b16 v[102:103], v246 offset:28672
	ds_read_b64_tr_b16 v[104:105], v247 offset:16384
	ds_read_b64_tr_b16 v[106:107], v247 offset:20480
	s_waitcnt lgkmcnt(11)
	ds_read_b64_tr_b16 v[108:109], v247 offset:24576
	ds_read_b64_tr_b16 v[110:111], v247 offset:28672
	ds_read_b64_tr_b16 v[112:113], v243 offset:37888
	ds_read_b64_tr_b16 v[114:115], v243 offset:39168
	s_waitcnt lgkmcnt(11)
	ds_read_b64_tr_b16 v[124:125], v243 offset:37920
	ds_read_b64_tr_b16 v[126:127], v243 offset:39200
	ds_read_b64_tr_b16 v[120:121], v243 offset:40448
	ds_read_b64_tr_b16 v[122:123], v243 offset:41728
	s_waitcnt lgkmcnt(11)
	ds_read_b64_tr_b16 v[128:129], v243 offset:40480
	ds_read_b64_tr_b16 v[130:131], v243 offset:41760
	ds_read_b128 v[64:67], v223 offset:16384
	ds_read_b128 v[68:71], v224 offset:16384
	global_load_dwordx4 v[156:159], v204, s[40:41] offset:2048
	s_waitcnt lgkmcnt(11)
	ds_read_b128 v[72:75], v225 offset:16384
	ds_read_b128 v[76:79], v226 offset:16384
	global_load_dwordx4 v[160:163], v205, s[40:41] offset:2048
	ds_read_b128 v[80:83], v223 offset:20480
	ds_read_b128 v[84:87], v224 offset:20480
	s_waitcnt lgkmcnt(11)
; __device__ __forceinline__ void phase_ssd(const Params& P, int seg, unsigned char* smem) {
;     ...
;         auto step = [&](int ci, Pre& R, const int par) {
;             const int row0 = chunk_row0(ci); unsigned char* sb = smem + par * T_BUF; float* acP = acS + par * 64;
;             const bf16* StR = StS + par * (T_STSZ / 2); bf16* StW = StS + (par ^ 1) * (T_STSZ / 2);
;             const float dec = __expf(R.alast);
;             { const float e2 = __expf(R.alast - R.acl);
; #pragma unroll
;               for (int i = 0; i < 2; ++i) { const int q = tid + 512 * i, l = q >> 4, c8 = q & 15; *(v4u*)(sb + T_CS + l * 272 + c8 * 16) = R.Cr[i]; *(v4u*)(sb + T_BS + l * 272 + c8 * 16) = R.Br[i]; }
;               const int l = tid >> 3, p4 = (tid & 7) * 4;
;               const float x0 = bflo(R.Xr.x) * R.dtl, x1 = bfhi(R.Xr.x) * R.dtl, x2 = bflo(R.Xr.y) * R.dtl, x3 = bfhi(R.Xr.y) * R.dtl;
;               v2u d; d.x = cvt_pk_bf16(x0, x1); d.y = cvt_pk_bf16(x2, x3); *(v2u*)(sb + T_XD + l * 80 + p4 * 2) = d;
;               v2u e; e.x = cvt_pk_bf16(x0 * e2, x1 * e2); e.y = cvt_pk_bf16(x2 * e2, x3 * e2); *(v2u*)(sb + T_XE + l * 80 + p4 * 2) = e;
;               *(v2u*)(sb + T_XS + l * 64 + p4 * 2) = R.Xr; *(v2u*)(sb + T_ZS + l * 64 + p4 * 2) = R.Zr;
;               if (w == 0) acP[lane] = R.aclane; }
;             BAR_LDS();
;             if (ci + 2 < nchunks) load_chunk(ci + 2, R);
;             bf16x8 cf[4];
; #pragma unroll
;             for (int k = 0; k < 4; ++k) cf[k] = *(const bf16x8*)(sb + T_CS + (lt * 16 + fr) * 272 + (k * 32 + fq * 8) * 2);
;             f32x4 yo = {0.f, 0.f, 0.f, 0.f};
; #pragma unroll
;             for (int k = 0; k < 4; ++k) { const bf16x8 bb = *(const bf16x8*)((const unsigned char*)StR + (pt * 16 + fr) * 272 + (k * 32 + fq * 8) * 2); yo = mfma16(cf[k], bb, yo); }
; { const f32x4 a4 = *(const f32x4*)(acP + lt * 16 + fq * 4);
; #pragma unroll
;               for (int j = 0; j < 4; ++j) yo[j] *= __expf(a4[j]); }
;             const float acl_fr = acP[lt * 16 + fr]; const int lrow = lt * 16 + fr;
; #pragma unroll
;             for (int t = 0; t < 2; ++t) {
;                 if (2 * t <= lt) {
;                     v2u xb0, xb1;
;                     { const unsigned a0 = lds0 + par * T_BUF + T_XD + (32 * t + 4 * fq + tq) * 80 + (pt * 16 + 4 * tp) * 2, a1 = a0 + 16 * 80; TR_ISSUE(xb0, a0); TR_ISSUE(xb1, a1); }
;                     float m[8];
	ds_read_b128 v[88:91], v225 offset:20480
	global_load_dwordx4 v[148:151], v204, s[40:41]
	ds_read_b128 v[92:95], v226 offset:20480
	v_mfma_f32_16x16x32_bf16 v[24:27], v[48:51], v[28:31], 0
	v_mfma_f32_16x16x32_bf16 v[24:27], v[52:55], v[32:35], v[24:27]
	global_load_dwordx4 v[152:155], v205, s[40:41]
	v_mfma_f32_16x16x32_bf16 v[24:27], v[56:59], v[40:43], v[24:27]
	v_mfma_f32_16x16x32_bf16 v[24:27], v[60:63], v[44:47], v[24:27]
	ds_read_b64_tr_b16 v[56:57], v234 offset:32768
	global_load_dwordx2 v[164:165], v206, s[40:41]
	ds_read_b64_tr_b16 v[58:59], v234 offset:34048
	v_mul_f32_e32 v8, v8, v174
	v_mul_f32_e32 v9, v9, v174
	global_load_dwordx2 v[166:167], v207, s[42:43] nt
	v_mul_f32_e32 v10, v10, v174
	v_mul_f32_e32 v11, v11, v174
	v_mul_f32_e32 v12, v12, v174
	global_load_dword v118, v208, s[44:45]
	v_mul_f32_e32 v13, v13, v174
	v_mul_f32_e32 v14, v14, v174
	v_mul_f32_e32 v15, v15, v174
	global_load_dword v168, v208, s[46:47]
	v_mul_f32_e32 v16, v16, v174
	v_mul_f32_e32 v17, v17, v174
	v_mul_f32_e32 v18, v18, v174
	global_load_dword v169, v209, s[46:47]
	v_mul_f32_e32 v19, v19, v174
	v_mul_f32_e32 v20, v20, v174
	v_mul_f32_e32 v21, v21, v174
	s_add_u32 s66, s54, 3
	s_cmp_lt_u32 s66, s39
	s_cselect_b32 s74, 0xc0000, 0
	s_cselect_b32 s75, 0x280000, 0
	s_cselect_b32 s76, 0x4000, 0
	s_add_u32 s40, s40, s74
	s_addc_u32 s41, s41, 0
	s_add_u32 s42, s42, s75
	s_addc_u32 s43, s43, 0
	s_add_u32 s44, s44, s76
	s_addc_u32 s45, s45, 0
	s_add_u32 s46, s46, s76
	s_addc_u32 s47, s47, 0
	v_mul_f32_e32 v22, v22, v174
	v_mul_f32_e32 v23, v23, v174
	v_mfma_f32_16x16x32_bf16 v[8:11], v[96:99], v[112:115], v[8:11]
	s_waitcnt lgkmcnt(14)
	v_mfma_f32_16x16x32_bf16 v[12:15], v[96:99], v[124:127], v[12:15]
	v_mfma_f32_16x16x32_bf16 v[16:19], v[104:107], v[112:115], v[16:19]
	v_mfma_f32_16x16x32_bf16 v[20:23], v[104:107], v[124:127], v[20:23]
	s_waitcnt lgkmcnt(12)
	v_mfma_f32_16x16x32_bf16 v[8:11], v[100:103], v[120:123], v[8:11]
	s_waitcnt lgkmcnt(10)
	v_mfma_f32_16x16x32_bf16 v[12:15], v[100:103], v[128:131], v[12:15]
	v_mfma_f32_16x16x32_bf16 v[16:19], v[108:111], v[120:123], v[16:19]
	v_mfma_f32_16x16x32_bf16 v[20:23], v[108:111], v[128:131], v[20:23]
	ds_read_b128 v[96:99], v232 offset:256
	ds_read_b128 v[100:103], v232 offset:320
	ds_read_b64 v[124:125], v236 offset:44160
	ds_read_b64 v[126:127], v236 offset:48768
	s_waitcnt lgkmcnt(13)
	v_mfma_f32_16x16x32_bf16 v[48:51], v[64:67], v[28:31], 0
	s_waitcnt lgkmcnt(9)
	v_mfma_f32_16x16x32_bf16 v[52:55], v[80:83], v[28:31], 0
	v_mfma_f32_16x16x32_bf16 v[48:51], v[68:71], v[32:35], v[48:51]
	s_waitcnt lgkmcnt(8)
	v_mfma_f32_16x16x32_bf16 v[52:55], v[84:87], v[32:35], v[52:55]
	v_mfma_f32_16x16x32_bf16 v[48:51], v[72:75], v[40:43], v[48:51]
	s_waitcnt lgkmcnt(7)
	v_mfma_f32_16x16x32_bf16 v[52:55], v[88:91], v[40:43], v[52:55]
	v_mfma_f32_16x16x32_bf16 v[48:51], v[76:79], v[44:47], v[48:51]
	s_waitcnt lgkmcnt(6)
	v_mfma_f32_16x16x32_bf16 v[52:55], v[92:95], v[44:47], v[52:55]
	v_exp_f32_e32 v195, v194
	s_nop 0
	v_mul_f32_e32 v24, v24, v195
	v_mul_f32_e32 v25, v25, v195
	v_mul_f32_e32 v26, v26, v195
	v_mul_f32_e32 v27, v27, v195
	v_cvt_pk_bf16_f32 v184, v8, v9
	v_cvt_pk_bf16_f32 v185, v10, v11
	v_cvt_pk_bf16_f32 v186, v12, v13
	v_cvt_pk_bf16_f32 v187, v14, v15
	v_cvt_pk_bf16_f32 v188, v16, v17
	v_cvt_pk_bf16_f32 v189, v18, v19
	v_cvt_pk_bf16_f32 v190, v20, v21
	v_cvt_pk_bf16_f32 v191, v22, v23
	ds_write_b64 v248, v[184:185]
	ds_write_b64 v248, v[186:187] offset:4096
	ds_write_b64 v249, v[188:189]
	ds_write_b64 v249, v[190:191] offset:4096
	s_waitcnt lgkmcnt(4)
	v_lshlrev_b32_e32 v112, 16, v126
	v_and_b32_e32 v113, 0xffff0000, v126
	v_lshlrev_b32_e32 v114, 16, v127
	v_and_b32_e32 v115, 0xffff0000, v127
	v_mul_f32_e32 v120, 0xbfb8aa3b, v112
	v_mul_f32_e32 v121, 0xbfb8aa3b, v113
	v_mul_f32_e32 v122, 0xbfb8aa3b, v114
	v_mul_f32_e32 v123, 0xbfb8aa3b, v115
	v_exp_f32_e32 v120, v120
	v_exp_f32_e32 v121, v121
	v_exp_f32_e32 v122, v122
	s_waitcnt vmcnt(10)
	v_exp_f32_e32 v123, v123
	ds_write_b128 v212, v[140:143]
	v_add_f32_e32 v120, 1.0, v120
	v_add_f32_e32 v121, 1.0, v121
	ds_write_b128 v212, v[144:147] offset:8192
	v_add_f32_e32 v122, 1.0, v122
	ds_write_b128 v212, v[132:135] offset:16384
	v_add_f32_e32 v123, 1.0, v123
	v_rcp_f32_e32 v120, v120
	ds_write_b128 v212, v[136:139] offset:24576
	v_rcp_f32_e32 v121, v121
	v_sub_f32_e32 v200, v117, v116
	v_rcp_f32_e32 v122, v122
	v_rcp_f32_e32 v123, v123
	v_mul_f32_e32 v200, 0x3fb8aa3b, v200
	v_mul_f32_e32 v112, v120, v112
	v_exp_f32_e32 v200, v200
	v_mul_f32_e32 v113, v121, v113
	v_mul_f32_e32 v114, v122, v114
	v_lshlrev_b32_e32 v196, 16, v4
	v_mul_f32_e32 v115, v123, v115
	v_and_b32_e32 v197, 0xffff0000, v4
	v_lshlrev_b32_e32 v120, 16, v124
	v_and_b32_e32 v121, 0xffff0000, v124
	v_lshlrev_b32_e32 v198, 16, v5
	v_lshlrev_b32_e32 v122, 16, v125
	v_and_b32_e32 v199, 0xffff0000, v5
	v_and_b32_e32 v123, 0xffff0000, v125
	v_sub_f32_e32 v184, v194, v96
	v_mul_f32_e32 v196, v196, v6
	v_sub_f32_e32 v185, v194, v97
	v_mul_f32_e32 v197, v197, v6
	v_sub_f32_e32 v186, v194, v98
	v_sub_f32_e32 v187, v194, v99
	v_mul_f32_e32 v198, v198, v6
	v_exp_f32_e32 v184, v184
	v_mul_f32_e32 v199, v199, v6
	v_exp_f32_e32 v185, v185
	v_exp_f32_e32 v186, v186
	v_cvt_pk_bf16_f32 v202, v196, v197
	v_exp_f32_e32 v187, v187
	v_cvt_pk_bf16_f32 v203, v198, v199
	v_mul_f32_e32 v184, v48, v184
	v_mul_f32_e32 v185, v49, v185
	ds_write_b64 v214, v[202:203] offset:32768
	v_mul_f32_e32 v186, v50, v186
	v_mul_f32_e32 v196, v196, v200
	v_mul_f32_e32 v187, v51, v187
	v_sub_f32_e32 v188, v194, v100
	v_mul_f32_e32 v197, v197, v200
	v_sub_f32_e32 v189, v194, v101
	v_mul_f32_e32 v198, v198, v200
	v_sub_f32_e32 v190, v194, v102
; __device__ __forceinline__ void phase_ssd(const Params& P, int seg, unsigned char* smem) {
;     ...
;         auto step = [&](int ci, Pre& R, const int par) {
;             const int row0 = chunk_row0(ci); unsigned char* sb = smem + par * T_BUF; float* acP = acS + par * 64;
;             const bf16* StR = StS + par * (T_STSZ / 2); bf16* StW = StS + (par ^ 1) * (T_STSZ / 2);
;             const float dec = __expf(R.alast);
;             { const float e2 = __expf(R.alast - R.acl);
; #pragma unroll
;               for (int i = 0; i < 2; ++i) { const int q = tid + 512 * i, l = q >> 4, c8 = q & 15; *(v4u*)(sb + T_CS + l * 272 + c8 * 16) = R.Cr[i]; *(v4u*)(sb + T_BS + l * 272 + c8 * 16) = R.Br[i]; }
;               const int l = tid >> 3, p4 = (tid & 7) * 4;
;               const float x0 = bflo(R.Xr.x) * R.dtl, x1 = bfhi(R.Xr.x) * R.dtl, x2 = bflo(R.Xr.y) * R.dtl, x3 = bfhi(R.Xr.y) * R.dtl;
;               v2u d; d.x = cvt_pk_bf16(x0, x1); d.y = cvt_pk_bf16(x2, x3); *(v2u*)(sb + T_XD + l * 80 + p4 * 2) = d;
;               v2u e; e.x = cvt_pk_bf16(x0 * e2, x1 * e2); e.y = cvt_pk_bf16(x2 * e2, x3 * e2); *(v2u*)(sb + T_XE + l * 80 + p4 * 2) = e;
;               *(v2u*)(sb + T_XS + l * 64 + p4 * 2) = R.Xr; *(v2u*)(sb + T_ZS + l * 64 + p4 * 2) = R.Zr;
;               if (w == 0) acP[lane] = R.aclane; }
;             BAR_LDS();
;             if (ci + 2 < nchunks) load_chunk(ci + 2, R);
;             bf16x8 cf[4];
; #pragma unroll
;             for (int k = 0; k < 4; ++k) cf[k] = *(const bf16x8*)(sb + T_CS + (lt * 16 + fr) * 272 + (k * 32 + fq * 8) * 2);
;             f32x4 yo = {0.f, 0.f, 0.f, 0.f};
; #pragma unroll
;             for (int k = 0; k < 4; ++k) { const bf16x8 bb = *(const bf16x8*)((const unsigned char*)StR + (pt * 16 + fr) * 272 + (k * 32 + fq * 8) * 2); yo = mfma16(cf[k], bb, yo); }
; { const f32x4 a4 = *(const f32x4*)(acP + lt * 16 + fq * 4);
; #pragma unroll
;               for (int j = 0; j < 4; ++j) yo[j] *= __expf(a4[j]); }
;             const float acl_fr = acP[lt * 16 + fr]; const int lrow = lt * 16 + fr;
; #pragma unroll
;             for (int t = 0; t < 2; ++t) {
;                 if (2 * t <= lt) {
;                     v2u xb0, xb1;
;                     { const unsigned a0 = lds0 + par * T_BUF + T_XD + (32 * t + 4 * fq + tq) * 80 + (pt * 16 + 4 * tp) * 2, a1 = a0 + 16 * 80; TR_ISSUE(xb0, a0); TR_ISSUE(xb1, a1); }
;                     float m[8];
	v_sub_f32_e32 v191, v194, v103
	v_mul_f32_e32 v199, v199, v200
	v_exp_f32_e32 v188, v188
	v_cvt_pk_bf16_f32 v192, v196, v197
	v_exp_f32_e32 v189, v189
	v_exp_f32_e32 v190, v190
	v_cvt_pk_bf16_f32 v193, v198, v199
	v_exp_f32_e32 v191, v191
	ds_write_b64 v214, v[192:193] offset:37888
	v_mul_f32_e32 v188, v52, v188
	v_mul_f32_e32 v189, v53, v189
	ds_write_b64 v216, v[4:5] offset:43008
	v_mul_f32_e32 v190, v54, v190
	ds_write_b64 v216, v[36:37] offset:47616
	v_mul_f32_e32 v191, v55, v191
	v_cndmask_b32_e64 v188, 0, v188, s[14:15]
	v_mul_f32_e32 v201, 0x3fb8aa3b, v116
	v_cndmask_b32_e64 v189, 0, v189, s[16:17]
	ds_write_b32 v218, v201
	v_cndmask_b32_e64 v190, 0, v190, s[22:23]
	v_cndmask_b32_e64 v191, 0, v191, s[34:35]
	v_mul_f32_e32 v174, 0x3fb8aa3b, v117
	v_cvt_pk_bf16_f32 v128, v184, v185
	v_exp_f32_e32 v174, v174
	v_cvt_pk_bf16_f32 v129, v186, v187
	v_cvt_pk_bf16_f32 v130, v188, v189
	v_cvt_pk_bf16_f32 v131, v190, v191
	s_nop 1
	v_mfma_f32_16x16x32_bf16 v[24:27], v[56:59], v[128:131], v[24:27]
	s_mul_i32 s65, s56, 0x2000
	s_add_u32 s65, s65, 0x304f1000
	s_add_u32 s48, s0, s65
	s_addc_u32 s49, s1, 0
	s_nop 3
	v_fma_f32 v184, s61, v120, v24
	v_fma_f32 v185, s61, v121, v25
	v_fma_f32 v186, s61, v122, v26
	v_fma_f32 v187, s61, v123, v27
	v_mul_f32_e32 v184, v184, v112
	v_mul_f32_e32 v185, v185, v113
	v_mul_f32_e32 v186, v186, v114
	v_mul_f32_e32 v187, v187, v115
	v_cvt_pk_bf16_f32 v170, v184, v185
	v_cvt_pk_bf16_f32 v171, v186, v187
	global_store_dwordx2 v210, v[170:171], s[48:49]
	s_add_u32 s65, s54, 1
	s_sub_u32 s65, s65, s60
	s_lshl_b32 s65, s65, 6
	s_add_u32 s56, s65, s20
	s_waitcnt lgkmcnt(0)
	s_barrier
	s_add_u32 s54, s54, 1
	s_cmp_lt_u32 s54, s39
	s_cbranch_scc1 .Lssd_loop1
	s_branch .Lssd_done
.Lssd_loop2:
	ds_read_b128 v[28:31], v219 offset:8192
	ds_read_b128 v[32:35], v220 offset:8192
	ds_read_b128 v[40:43], v221 offset:8192
	ds_read_b128 v[44:47], v222 offset:8192
	ds_read_b128 v[48:51], v227
	ds_read_b128 v[52:55], v228
	ds_read_b128 v[56:59], v229
	ds_read_b128 v[60:63], v230
	ds_read_b32 v194, v231 offset:128
	ds_read_b128 v[64:67], v219 offset:16384
	ds_read_b128 v[68:71], v220 offset:16384
	ds_read_b128 v[72:75], v221 offset:16384
	ds_read_b128 v[76:79], v222 offset:16384
	ds_read_b128 v[80:83], v219 offset:20480
	ds_read_b128 v[84:87], v220 offset:20480
	global_load_dwordx4 v[140:143], v204, s[40:41] offset:2048
	s_waitcnt lgkmcnt(11)
	ds_read_b128 v[88:91], v221 offset:20480
	ds_read_b128 v[92:95], v222 offset:20480
	global_load_dwordx4 v[144:147], v205, s[40:41] offset:2048
	ds_read_b128 v[96:99], v232
	ds_read_b128 v[100:103], v232 offset:64
	s_waitcnt lgkmcnt(11)
	ds_read_b64 v[124:125], v235 offset:45312
	global_load_dwordx4 v[132:135], v204, s[40:41]
	ds_read_b64 v[126:127], v235 offset:49920
	v_mfma_f32_16x16x32_bf16 v[24:27], v[48:51], v[28:31], 0
	v_mfma_f32_16x16x32_bf16 v[24:27], v[52:55], v[32:35], v[24:27]
	global_load_dwordx4 v[136:139], v205, s[40:41]
	v_mfma_f32_16x16x32_bf16 v[24:27], v[56:59], v[40:43], v[24:27]
	v_mfma_f32_16x16x32_bf16 v[24:27], v[60:63], v[44:47], v[24:27]
	global_load_dwordx2 v[4:5], v206, s[40:41]
	ds_read_b64_tr_b16 v[56:57], v233 offset:32768
	ds_read_b64_tr_b16 v[58:59], v233 offset:34048
	s_waitcnt lgkmcnt(13)
	v_mfma_f32_16x16x32_bf16 v[48:51], v[64:67], v[28:31], 0
	global_load_dwordx2 v[36:37], v207, s[42:43] nt
	s_waitcnt lgkmcnt(9)
	v_mfma_f32_16x16x32_bf16 v[52:55], v[80:83], v[28:31], 0
	v_mfma_f32_16x16x32_bf16 v[48:51], v[68:71], v[32:35], v[48:51]
	s_waitcnt lgkmcnt(8)
	v_mfma_f32_16x16x32_bf16 v[52:55], v[84:87], v[32:35], v[52:55]
	global_load_dword v6, v208, s[44:45]
	v_mfma_f32_16x16x32_bf16 v[48:51], v[72:75], v[40:43], v[48:51]
	s_waitcnt lgkmcnt(7)
	v_mfma_f32_16x16x32_bf16 v[52:55], v[88:91], v[40:43], v[52:55]
	global_load_dword v116, v208, s[46:47]
	v_mfma_f32_16x16x32_bf16 v[48:51], v[76:79], v[44:47], v[48:51]
	s_waitcnt lgkmcnt(6)
	v_mfma_f32_16x16x32_bf16 v[52:55], v[92:95], v[44:47], v[52:55]
	ds_read_b128 v[64:67], v219 offset:24576
	global_load_dword v117, v209, s[46:47]
	ds_read_b128 v[68:71], v220 offset:24576
	ds_read_b128 v[72:75], v221 offset:24576
	ds_read_b128 v[76:79], v222 offset:24576
	s_add_u32 s66, s54, 3
	s_cmp_lt_u32 s66, s39
	s_cselect_b32 s74, 0xc0000, 0
	s_cselect_b32 s75, 0x280000, 0
	s_cselect_b32 s76, 0x4000, 0
	s_add_u32 s40, s40, s74
	s_addc_u32 s41, s41, 0
	s_add_u32 s42, s42, s75
	s_addc_u32 s43, s43, 0
	s_add_u32 s44, s44, s76
	s_addc_u32 s45, s45, 0
	s_add_u32 s46, s46, s76
	s_addc_u32 s47, s47, 0
	ds_read_b64_tr_b16 v[60:61], v233 offset:35328
	ds_read_b64_tr_b16 v[62:63], v233 offset:36608
	v_exp_f32_e32 v195, v194
	s_nop 0
	v_mul_f32_e32 v24, v24, v195
	v_mul_f32_e32 v25, v25, v195
	v_mul_f32_e32 v26, v26, v195
	v_mul_f32_e32 v27, v27, v195
	s_waitcnt lgkmcnt(8)
	v_lshlrev_b32_e32 v112, 16, v126
	v_and_b32_e32 v113, 0xffff0000, v126
	v_lshlrev_b32_e32 v114, 16, v127
	v_and_b32_e32 v115, 0xffff0000, v127
	v_mul_f32_e32 v120, 0xbfb8aa3b, v112
	v_mul_f32_e32 v121, 0xbfb8aa3b, v113
	v_mul_f32_e32 v122, 0xbfb8aa3b, v114
	v_mul_f32_e32 v123, 0xbfb8aa3b, v115
	v_exp_f32_e32 v120, v120
	v_exp_f32_e32 v121, v121
	v_exp_f32_e32 v122, v122
	v_exp_f32_e32 v123, v123
	v_add_f32_e32 v120, 1.0, v120
	v_add_f32_e32 v121, 1.0, v121
	v_add_f32_e32 v122, 1.0, v122
	v_add_f32_e32 v123, 1.0, v123
	v_rcp_f32_e32 v120, v120
	v_rcp_f32_e32 v121, v121
	v_rcp_f32_e32 v122, v122
	v_rcp_f32_e32 v123, v123
	v_mul_f32_e32 v112, v120, v112
	v_mul_f32_e32 v113, v121, v113
	v_mul_f32_e32 v114, v122, v114
	v_mul_f32_e32 v115, v123, v115
	v_lshlrev_b32_e32 v120, 16, v124
	v_and_b32_e32 v121, 0xffff0000, v124
	v_lshlrev_b32_e32 v122, 16, v125
	v_and_b32_e32 v123, 0xffff0000, v125
	v_sub_f32_e32 v184, v194, v96
	v_sub_f32_e32 v185, v194, v97
	v_sub_f32_e32 v186, v194, v98
	v_sub_f32_e32 v187, v194, v99
	v_exp_f32_e32 v184, v184
	v_exp_f32_e32 v185, v185
	v_exp_f32_e32 v186, v186
	v_exp_f32_e32 v187, v187
	v_mul_f32_e32 v184, v48, v184
	s_waitcnt vmcnt(10)
; __device__ __forceinline__ void phase_ssd(const Params& P, int seg, unsigned char* smem) {
;     ...
;         auto step = [&](int ci, Pre& R, const int par) {
;             const int row0 = chunk_row0(ci); unsigned char* sb = smem + par * T_BUF; float* acP = acS + par * 64;
;             const bf16* StR = StS + par * (T_STSZ / 2); bf16* StW = StS + (par ^ 1) * (T_STSZ / 2);
;             const float dec = __expf(R.alast);
;             { const float e2 = __expf(R.alast - R.acl);
; #pragma unroll
;               for (int i = 0; i < 2; ++i) { const int q = tid + 512 * i, l = q >> 4, c8 = q & 15; *(v4u*)(sb + T_CS + l * 272 + c8 * 16) = R.Cr[i]; *(v4u*)(sb + T_BS + l * 272 + c8 * 16) = R.Br[i]; }
;               const int l = tid >> 3, p4 = (tid & 7) * 4;
;               const float x0 = bflo(R.Xr.x) * R.dtl, x1 = bfhi(R.Xr.x) * R.dtl, x2 = bflo(R.Xr.y) * R.dtl, x3 = bfhi(R.Xr.y) * R.dtl;
;               v2u d; d.x = cvt_pk_bf16(x0, x1); d.y = cvt_pk_bf16(x2, x3); *(v2u*)(sb + T_XD + l * 80 + p4 * 2) = d;
;               v2u e; e.x = cvt_pk_bf16(x0 * e2, x1 * e2); e.y = cvt_pk_bf16(x2 * e2, x3 * e2); *(v2u*)(sb + T_XE + l * 80 + p4 * 2) = e;
;               *(v2u*)(sb + T_XS + l * 64 + p4 * 2) = R.Xr; *(v2u*)(sb + T_ZS + l * 64 + p4 * 2) = R.Zr;
;               if (w == 0) acP[lane] = R.aclane; }
;             BAR_LDS();
;             if (ci + 2 < nchunks) load_chunk(ci + 2, R);
;             bf16x8 cf[4];
; #pragma unroll
;             for (int k = 0; k < 4; ++k) cf[k] = *(const bf16x8*)(sb + T_CS + (lt * 16 + fr) * 272 + (k * 32 + fq * 8) * 2);
;             f32x4 yo = {0.f, 0.f, 0.f, 0.f};
; #pragma unroll
;             for (int k = 0; k < 4; ++k) { const bf16x8 bb = *(const bf16x8*)((const unsigned char*)StR + (pt * 16 + fr) * 272 + (k * 32 + fq * 8) * 2); yo = mfma16(cf[k], bb, yo); }
; { const f32x4 a4 = *(const f32x4*)(acP + lt * 16 + fq * 4);
; #pragma unroll
;               for (int j = 0; j < 4; ++j) yo[j] *= __expf(a4[j]); }
;             const float acl_fr = acP[lt * 16 + fr]; const int lrow = lt * 16 + fr;
; #pragma unroll
;             for (int t = 0; t < 2; ++t) {
;                 if (2 * t <= lt) {
;                     v2u xb0, xb1;
;                     { const unsigned a0 = lds0 + par * T_BUF + T_XD + (32 * t + 4 * fq + tq) * 80 + (pt * 16 + 4 * tp) * 2, a1 = a0 + 16 * 80; TR_ISSUE(xb0, a0); TR_ISSUE(xb1, a1); }
;                     float m[8];
	v_mul_f32_e32 v185, v49, v185
	v_mul_f32_e32 v186, v50, v186
	ds_write_b128 v213, v[156:159]
	v_mul_f32_e32 v187, v51, v187
	ds_write_b128 v213, v[160:163] offset:8192
	v_sub_f32_e32 v188, v194, v100
	ds_write_b128 v213, v[148:151] offset:16384
	v_sub_f32_e32 v189, v194, v101
	v_sub_f32_e32 v190, v194, v102
	ds_write_b128 v213, v[152:155] offset:24576
	v_sub_f32_e32 v191, v194, v103
	v_sub_f32_e32 v200, v169, v168
	v_exp_f32_e32 v188, v188
	v_mul_f32_e32 v200, 0x3fb8aa3b, v200
	v_exp_f32_e32 v189, v189
	v_exp_f32_e32 v190, v190
	v_exp_f32_e32 v200, v200
	v_exp_f32_e32 v191, v191
	v_lshlrev_b32_e32 v196, 16, v164
	v_mul_f32_e32 v188, v52, v188
	v_and_b32_e32 v197, 0xffff0000, v164
	v_mul_f32_e32 v189, v53, v189
	v_mul_f32_e32 v190, v54, v190
	v_lshlrev_b32_e32 v198, 16, v165
	v_mul_f32_e32 v191, v55, v191
	v_and_b32_e32 v199, 0xffff0000, v165
	v_cvt_pk_bf16_f32 v128, v184, v185
	v_cvt_pk_bf16_f32 v129, v186, v187
	v_mul_f32_e32 v196, v196, v118
	v_cvt_pk_bf16_f32 v130, v188, v189
	v_mul_f32_e32 v197, v197, v118
	v_cvt_pk_bf16_f32 v131, v190, v191
	v_mul_f32_e32 v198, v198, v118
	s_waitcnt lgkmcnt(10)
	v_mfma_f32_16x16x32_bf16 v[24:27], v[56:59], v[128:131], v[24:27]
	ds_read_b128 v[96:99], v232 offset:128
	v_mul_f32_e32 v199, v199, v118
	s_waitcnt lgkmcnt(10)
	v_mfma_f32_16x16x32_bf16 v[48:51], v[64:67], v[28:31], 0
	v_cvt_pk_bf16_f32 v202, v196, v197
	s_waitcnt lgkmcnt(9)
	v_mfma_f32_16x16x32_bf16 v[48:51], v[68:71], v[32:35], v[48:51]
	v_cvt_pk_bf16_f32 v203, v198, v199
	s_waitcnt lgkmcnt(8)
	v_mfma_f32_16x16x32_bf16 v[48:51], v[72:75], v[40:43], v[48:51]
	s_waitcnt lgkmcnt(7)
	v_mfma_f32_16x16x32_bf16 v[48:51], v[76:79], v[44:47], v[48:51]
	ds_write_b64 v215, v[202:203] offset:32768
	s_waitcnt lgkmcnt(1)
	v_sub_f32_e32 v184, v194, v96
	v_mul_f32_e32 v196, v196, v200
	v_sub_f32_e32 v185, v194, v97
	v_mul_f32_e32 v197, v197, v200
	v_sub_f32_e32 v186, v194, v98
	v_sub_f32_e32 v187, v194, v99
	v_mul_f32_e32 v198, v198, v200
	v_exp_f32_e32 v184, v184
	v_mul_f32_e32 v199, v199, v200
	v_exp_f32_e32 v185, v185
	v_cvt_pk_bf16_f32 v192, v196, v197
	v_exp_f32_e32 v186, v186
	v_exp_f32_e32 v187, v187
	v_cvt_pk_bf16_f32 v193, v198, v199
	v_mul_f32_e32 v184, v48, v184
	ds_write_b64 v215, v[192:193] offset:37888
	v_mul_f32_e32 v185, v49, v185
	ds_write_b64 v217, v[164:165] offset:43008
	v_mul_f32_e32 v186, v50, v186
	v_mul_f32_e32 v187, v51, v187
	ds_write_b64 v217, v[166:167] offset:47616
	v_cndmask_b32_e64 v184, 0, v184, s[14:15]
	v_mul_f32_e32 v201, 0x3fb8aa3b, v168
	v_cndmask_b32_e64 v185, 0, v185, s[16:17]
	ds_write_b32 v218, v201 offset:256
	v_cndmask_b32_e64 v186, 0, v186, s[22:23]
	v_cndmask_b32_e64 v187, 0, v187, s[34:35]
	v_mul_f32_e32 v174, 0x3fb8aa3b, v169
	v_cvt_pk_bf16_f32 v128, v184, v185
	v_exp_f32_e32 v174, v174
	v_cvt_pk_bf16_f32 v129, v186, v187
	v_mov_b32_e32 v130, 0
	v_mov_b32_e32 v131, 0
	s_nop 1
	v_mfma_f32_16x16x32_bf16 v[24:27], v[60:63], v[128:131], v[24:27]
	s_mul_i32 s65, s56, 0x2000
	s_add_u32 s65, s65, 0x304f1000
	s_add_u32 s48, s0, s65
	s_addc_u32 s49, s1, 0
	s_nop 3
	v_fma_f32 v184, s61, v120, v24
	v_fma_f32 v185, s61, v121, v25
	v_fma_f32 v186, s61, v122, v26
	v_fma_f32 v187, s61, v123, v27
	v_mul_f32_e32 v184, v184, v112
	v_mul_f32_e32 v185, v185, v113
	v_mul_f32_e32 v186, v186, v114
	v_mul_f32_e32 v187, v187, v115
	v_cvt_pk_bf16_f32 v170, v184, v185
	v_cvt_pk_bf16_f32 v171, v186, v187
	global_store_dwordx2 v210, v[170:171], s[48:49]
	s_add_u32 s65, s54, 1
	s_sub_u32 s65, s65, s60
	s_lshl_b32 s65, s65, 6
	s_add_u32 s56, s65, s20
	s_waitcnt lgkmcnt(0)
	s_barrier
	s_add_u32 s54, s54, 1
	s_cmp_ge_u32 s54, s39
	s_cbranch_scc1 .Lssd_done
	ds_read_b128 v[28:31], v223 offset:8192
	ds_read_b128 v[32:35], v224 offset:8192
	ds_read_b128 v[40:43], v225 offset:8192
	ds_read_b128 v[44:47], v226 offset:8192
	ds_read_b128 v[48:51], v227 offset:8192
	ds_read_b128 v[52:55], v228 offset:8192
	ds_read_b128 v[56:59], v229 offset:8192
	ds_read_b128 v[60:63], v230 offset:8192
	ds_read_b32 v194, v231 offset:384
	ds_read_b128 v[64:67], v223 offset:16384
	ds_read_b128 v[68:71], v224 offset:16384
	ds_read_b128 v[72:75], v225 offset:16384
	ds_read_b128 v[76:79], v226 offset:16384
	ds_read_b128 v[80:83], v223 offset:20480
	ds_read_b128 v[84:87], v224 offset:20480
	global_load_dwordx4 v[156:159], v204, s[40:41] offset:2048
	s_waitcnt lgkmcnt(11)
	ds_read_b128 v[88:91], v225 offset:20480
	ds_read_b128 v[92:95], v226 offset:20480
	global_load_dwordx4 v[160:163], v205, s[40:41] offset:2048
	ds_read_b128 v[96:99], v232 offset:256
	ds_read_b128 v[100:103], v232 offset:320
	s_waitcnt lgkmcnt(11)
	ds_read_b64 v[124:125], v236 offset:45312
	global_load_dwordx4 v[148:151], v204, s[40:41]
	ds_read_b64 v[126:127], v236 offset:49920
	v_mfma_f32_16x16x32_bf16 v[24:27], v[48:51], v[28:31], 0
	v_mfma_f32_16x16x32_bf16 v[24:27], v[52:55], v[32:35], v[24:27]
	global_load_dwordx4 v[152:155], v205, s[40:41]
	v_mfma_f32_16x16x32_bf16 v[24:27], v[56:59], v[40:43], v[24:27]
	v_mfma_f32_16x16x32_bf16 v[24:27], v[60:63], v[44:47], v[24:27]
	global_load_dwordx2 v[164:165], v206, s[40:41]
	ds_read_b64_tr_b16 v[56:57], v234 offset:32768
	ds_read_b64_tr_b16 v[58:59], v234 offset:34048
	s_waitcnt lgkmcnt(13)
	v_mfma_f32_16x16x32_bf16 v[48:51], v[64:67], v[28:31], 0
	global_load_dwordx2 v[166:167], v207, s[42:43] nt
	s_waitcnt lgkmcnt(9)
	v_mfma_f32_16x16x32_bf16 v[52:55], v[80:83], v[28:31], 0
	v_mfma_f32_16x16x32_bf16 v[48:51], v[68:71], v[32:35], v[48:51]
	s_waitcnt lgkmcnt(8)
	v_mfma_f32_16x16x32_bf16 v[52:55], v[84:87], v[32:35], v[52:55]
	global_load_dword v118, v208, s[44:45]
	v_mfma_f32_16x16x32_bf16 v[48:51], v[72:75], v[40:43], v[48:51]
	s_waitcnt lgkmcnt(7)
; __device__ __forceinline__ void phase_ssd(const Params& P, int seg, unsigned char* smem) {
;     ...
;         auto step = [&](int ci, Pre& R, const int par) {
;             const int row0 = chunk_row0(ci); unsigned char* sb = smem + par * T_BUF; float* acP = acS + par * 64;
;             const bf16* StR = StS + par * (T_STSZ / 2); bf16* StW = StS + (par ^ 1) * (T_STSZ / 2);
;             const float dec = __expf(R.alast);
;             { const float e2 = __expf(R.alast - R.acl);
; #pragma unroll
;               for (int i = 0; i < 2; ++i) { const int q = tid + 512 * i, l = q >> 4, c8 = q & 15; *(v4u*)(sb + T_CS + l * 272 + c8 * 16) = R.Cr[i]; *(v4u*)(sb + T_BS + l * 272 + c8 * 16) = R.Br[i]; }
;               const int l = tid >> 3, p4 = (tid & 7) * 4;
;               const float x0 = bflo(R.Xr.x) * R.dtl, x1 = bfhi(R.Xr.x) * R.dtl, x2 = bflo(R.Xr.y) * R.dtl, x3 = bfhi(R.Xr.y) * R.dtl;
;               v2u d; d.x = cvt_pk_bf16(x0, x1); d.y = cvt_pk_bf16(x2, x3); *(v2u*)(sb + T_XD + l * 80 + p4 * 2) = d;
;               v2u e; e.x = cvt_pk_bf16(x0 * e2, x1 * e2); e.y = cvt_pk_bf16(x2 * e2, x3 * e2); *(v2u*)(sb + T_XE + l * 80 + p4 * 2) = e;
;               *(v2u*)(sb + T_XS + l * 64 + p4 * 2) = R.Xr; *(v2u*)(sb + T_ZS + l * 64 + p4 * 2) = R.Zr;
;               if (w == 0) acP[lane] = R.aclane; }
;             BAR_LDS();
;             if (ci + 2 < nchunks) load_chunk(ci + 2, R);
;             bf16x8 cf[4];
; #pragma unroll
;             for (int k = 0; k < 4; ++k) cf[k] = *(const bf16x8*)(sb + T_CS + (lt * 16 + fr) * 272 + (k * 32 + fq * 8) * 2);
;             f32x4 yo = {0.f, 0.f, 0.f, 0.f};
; #pragma unroll
;             for (int k = 0; k < 4; ++k) { const bf16x8 bb = *(const bf16x8*)((const unsigned char*)StR + (pt * 16 + fr) * 272 + (k * 32 + fq * 8) * 2); yo = mfma16(cf[k], bb, yo); }
; { const f32x4 a4 = *(const f32x4*)(acP + lt * 16 + fq * 4);
; #pragma unroll
;               for (int j = 0; j < 4; ++j) yo[j] *= __expf(a4[j]); }
;             const float acl_fr = acP[lt * 16 + fr]; const int lrow = lt * 16 + fr;
; #pragma unroll
;             for (int t = 0; t < 2; ++t) {
;                 if (2 * t <= lt) {
;                     v2u xb0, xb1;
;                     { const unsigned a0 = lds0 + par * T_BUF + T_XD + (32 * t + 4 * fq + tq) * 80 + (pt * 16 + 4 * tp) * 2, a1 = a0 + 16 * 80; TR_ISSUE(xb0, a0); TR_ISSUE(xb1, a1); }
;                     float m[8];
	v_mfma_f32_16x16x32_bf16 v[52:55], v[88:91], v[40:43], v[52:55]
	global_load_dword v168, v208, s[46:47]
	v_mfma_f32_16x16x32_bf16 v[48:51], v[76:79], v[44:47], v[48:51]
	s_waitcnt lgkmcnt(6)
	v_mfma_f32_16x16x32_bf16 v[52:55], v[92:95], v[44:47], v[52:55]
	ds_read_b128 v[64:67], v223 offset:24576
	global_load_dword v169, v209, s[46:47]
	ds_read_b128 v[68:71], v224 offset:24576
	ds_read_b128 v[72:75], v225 offset:24576
	ds_read_b128 v[76:79], v226 offset:24576
	s_add_u32 s66, s54, 3
	s_cmp_lt_u32 s66, s39
	s_cselect_b32 s74, 0xc0000, 0
	s_cselect_b32 s75, 0x280000, 0
	s_cselect_b32 s76, 0x4000, 0
	s_add_u32 s40, s40, s74
	s_addc_u32 s41, s41, 0
	s_add_u32 s42, s42, s75
	s_addc_u32 s43, s43, 0
	s_add_u32 s44, s44, s76
	s_addc_u32 s45, s45, 0
	s_add_u32 s46, s46, s76
	s_addc_u32 s47, s47, 0
	ds_read_b64_tr_b16 v[60:61], v234 offset:35328
	ds_read_b64_tr_b16 v[62:63], v234 offset:36608
	v_exp_f32_e32 v195, v194
	s_nop 0
	v_mul_f32_e32 v24, v24, v195
	v_mul_f32_e32 v25, v25, v195
	v_mul_f32_e32 v26, v26, v195
	v_mul_f32_e32 v27, v27, v195
	s_waitcnt lgkmcnt(8)
	v_lshlrev_b32_e32 v112, 16, v126
	v_and_b32_e32 v113, 0xffff0000, v126
	v_lshlrev_b32_e32 v114, 16, v127
	v_and_b32_e32 v115, 0xffff0000, v127
	v_mul_f32_e32 v120, 0xbfb8aa3b, v112
	v_mul_f32_e32 v121, 0xbfb8aa3b, v113
	v_mul_f32_e32 v122, 0xbfb8aa3b, v114
	v_mul_f32_e32 v123, 0xbfb8aa3b, v115
	v_exp_f32_e32 v120, v120
	v_exp_f32_e32 v121, v121
	v_exp_f32_e32 v122, v122
	v_exp_f32_e32 v123, v123
	v_add_f32_e32 v120, 1.0, v120
	v_add_f32_e32 v121, 1.0, v121
	v_add_f32_e32 v122, 1.0, v122
	v_add_f32_e32 v123, 1.0, v123
	v_rcp_f32_e32 v120, v120
	v_rcp_f32_e32 v121, v121
	v_rcp_f32_e32 v122, v122
	v_rcp_f32_e32 v123, v123
	v_mul_f32_e32 v112, v120, v112
	v_mul_f32_e32 v113, v121, v113
	v_mul_f32_e32 v114, v122, v114
	v_mul_f32_e32 v115, v123, v115
	v_lshlrev_b32_e32 v120, 16, v124
	v_and_b32_e32 v121, 0xffff0000, v124
	v_lshlrev_b32_e32 v122, 16, v125
	v_and_b32_e32 v123, 0xffff0000, v125
	v_sub_f32_e32 v184, v194, v96
	v_sub_f32_e32 v185, v194, v97
	v_sub_f32_e32 v186, v194, v98
	v_sub_f32_e32 v187, v194, v99
	v_exp_f32_e32 v184, v184
	v_exp_f32_e32 v185, v185
	v_exp_f32_e32 v186, v186
	v_exp_f32_e32 v187, v187
	v_mul_f32_e32 v184, v48, v184
	s_waitcnt vmcnt(10)
	v_mul_f32_e32 v185, v49, v185
	v_mul_f32_e32 v186, v50, v186
	ds_write_b128 v212, v[140:143]
	v_mul_f32_e32 v187, v51, v187
	ds_write_b128 v212, v[144:147] offset:8192
	v_sub_f32_e32 v188, v194, v100
	ds_write_b128 v212, v[132:135] offset:16384
	v_sub_f32_e32 v189, v194, v101
	v_sub_f32_e32 v190, v194, v102
	ds_write_b128 v212, v[136:139] offset:24576
	v_sub_f32_e32 v191, v194, v103
	v_sub_f32_e32 v200, v117, v116
	v_exp_f32_e32 v188, v188
	v_mul_f32_e32 v200, 0x3fb8aa3b, v200
	v_exp_f32_e32 v189, v189
	v_exp_f32_e32 v190, v190
	v_exp_f32_e32 v200, v200
	v_exp_f32_e32 v191, v191
	v_lshlrev_b32_e32 v196, 16, v4
	v_mul_f32_e32 v188, v52, v188
	v_and_b32_e32 v197, 0xffff0000, v4
	v_mul_f32_e32 v189, v53, v189
	v_mul_f32_e32 v190, v54, v190
	v_lshlrev_b32_e32 v198, 16, v5
	v_mul_f32_e32 v191, v55, v191
	v_and_b32_e32 v199, 0xffff0000, v5
	v_cvt_pk_bf16_f32 v128, v184, v185
	v_cvt_pk_bf16_f32 v129, v186, v187
	v_mul_f32_e32 v196, v196, v6
	v_cvt_pk_bf16_f32 v130, v188, v189
	v_mul_f32_e32 v197, v197, v6
	v_cvt_pk_bf16_f32 v131, v190, v191
	v_mul_f32_e32 v198, v198, v6
	s_waitcnt lgkmcnt(10)
	v_mfma_f32_16x16x32_bf16 v[24:27], v[56:59], v[128:131], v[24:27]
	ds_read_b128 v[96:99], v232 offset:384
	v_mul_f32_e32 v199, v199, v6
	s_waitcnt lgkmcnt(10)
	v_mfma_f32_16x16x32_bf16 v[48:51], v[64:67], v[28:31], 0
	v_cvt_pk_bf16_f32 v202, v196, v197
	s_waitcnt lgkmcnt(9)
	v_mfma_f32_16x16x32_bf16 v[48:51], v[68:71], v[32:35], v[48:51]
	v_cvt_pk_bf16_f32 v203, v198, v199
	s_waitcnt lgkmcnt(8)
	v_mfma_f32_16x16x32_bf16 v[48:51], v[72:75], v[40:43], v[48:51]
	s_waitcnt lgkmcnt(7)
	v_mfma_f32_16x16x32_bf16 v[48:51], v[76:79], v[44:47], v[48:51]
	ds_write_b64 v214, v[202:203] offset:32768
	s_waitcnt lgkmcnt(1)
	v_sub_f32_e32 v184, v194, v96
	v_mul_f32_e32 v196, v196, v200
	v_sub_f32_e32 v185, v194, v97
	v_mul_f32_e32 v197, v197, v200
	v_sub_f32_e32 v186, v194, v98
	v_sub_f32_e32 v187, v194, v99
	v_mul_f32_e32 v198, v198, v200
	v_exp_f32_e32 v184, v184
	v_mul_f32_e32 v199, v199, v200
	v_exp_f32_e32 v185, v185
	v_cvt_pk_bf16_f32 v192, v196, v197
	v_exp_f32_e32 v186, v186
	v_exp_f32_e32 v187, v187
	v_cvt_pk_bf16_f32 v193, v198, v199
	v_mul_f32_e32 v184, v48, v184
	ds_write_b64 v214, v[192:193] offset:37888
	v_mul_f32_e32 v185, v49, v185
	ds_write_b64 v216, v[4:5] offset:43008
	v_mul_f32_e32 v186, v50, v186
	v_mul_f32_e32 v187, v51, v187
	ds_write_b64 v216, v[36:37] offset:47616
	v_cndmask_b32_e64 v184, 0, v184, s[14:15]
	v_mul_f32_e32 v201, 0x3fb8aa3b, v116
	v_cndmask_b32_e64 v185, 0, v185, s[16:17]
	ds_write_b32 v218, v201
	v_cndmask_b32_e64 v186, 0, v186, s[22:23]
	v_cndmask_b32_e64 v187, 0, v187, s[34:35]
	v_mul_f32_e32 v174, 0x3fb8aa3b, v117
	v_cvt_pk_bf16_f32 v128, v184, v185
	v_exp_f32_e32 v174, v174
	v_cvt_pk_bf16_f32 v129, v186, v187
	v_mov_b32_e32 v130, 0
	v_mov_b32_e32 v131, 0
	s_nop 1
	v_mfma_f32_16x16x32_bf16 v[24:27], v[60:63], v[128:131], v[24:27]
	s_mul_i32 s65, s56, 0x2000
	s_add_u32 s65, s65, 0x304f1000
	s_add_u32 s48, s0, s65
	s_addc_u32 s49, s1, 0
	s_nop 3
	v_fma_f32 v184, s61, v120, v24
	v_fma_f32 v185, s61, v121, v25
	v_fma_f32 v186, s61, v122, v26
	v_fma_f32 v187, s61, v123, v27
	v_mul_f32_e32 v184, v184, v112
	v_mul_f32_e32 v185, v185, v113
	v_mul_f32_e32 v186, v186, v114
	v_mul_f32_e32 v187, v187, v115
	v_cvt_pk_bf16_f32 v170, v184, v185
	v_cvt_pk_bf16_f32 v171, v186, v187
	global_store_dwordx2 v210, v[170:171], s[48:49]
	s_add_u32 s65, s54, 1
	s_sub_u32 s65, s65, s60
	s_lshl_b32 s65, s65, 6
	s_add_u32 s56, s65, s20
	s_waitcnt lgkmcnt(0)
	s_barrier
	s_add_u32 s54, s54, 1
	s_cmp_lt_u32 s54, s39
	s_cbranch_scc1 .Lssd_loop2
	s_branch .Lssd_done
; __device__ __forceinline__ void phase_ssd(const Params& P, int seg, unsigned char* smem) {
;     ...
;         auto step = [&](int ci, Pre& R, const int par) {
;             const int row0 = chunk_row0(ci); unsigned char* sb = smem + par * T_BUF; float* acP = acS + par * 64;
;             const bf16* StR = StS + par * (T_STSZ / 2); bf16* StW = StS + (par ^ 1) * (T_STSZ / 2);
;             const float dec = __expf(R.alast);
;             { const float e2 = __expf(R.alast - R.acl);
; #pragma unroll
;               for (int i = 0; i < 2; ++i) { const int q = tid + 512 * i, l = q >> 4, c8 = q & 15; *(v4u*)(sb + T_CS + l * 272 + c8 * 16) = R.Cr[i]; *(v4u*)(sb + T_BS + l * 272 + c8 * 16) = R.Br[i]; }
;               const int l = tid >> 3, p4 = (tid & 7) * 4;
;               const float x0 = bflo(R.Xr.x) * R.dtl, x1 = bfhi(R.Xr.x) * R.dtl, x2 = bflo(R.Xr.y) * R.dtl, x3 = bfhi(R.Xr.y) * R.dtl;
;               v2u d; d.x = cvt_pk_bf16(x0, x1); d.y = cvt_pk_bf16(x2, x3); *(v2u*)(sb + T_XD + l * 80 + p4 * 2) = d;
;               v2u e; e.x = cvt_pk_bf16(x0 * e2, x1 * e2); e.y = cvt_pk_bf16(x2 * e2, x3 * e2); *(v2u*)(sb + T_XE + l * 80 + p4 * 2) = e;
;               *(v2u*)(sb + T_XS + l * 64 + p4 * 2) = R.Xr; *(v2u*)(sb + T_ZS + l * 64 + p4 * 2) = R.Zr;
;               if (w == 0) acP[lane] = R.aclane; }
;             BAR_LDS();
;             if (ci + 2 < nchunks) load_chunk(ci + 2, R);
;             bf16x8 cf[4];
; #pragma unroll
;             for (int k = 0; k < 4; ++k) cf[k] = *(const bf16x8*)(sb + T_CS + (lt * 16 + fr) * 272 + (k * 32 + fq * 8) * 2);
;             f32x4 yo = {0.f, 0.f, 0.f, 0.f};
; #pragma unroll
;             for (int k = 0; k < 4; ++k) { const bf16x8 bb = *(const bf16x8*)((const unsigned char*)StR + (pt * 16 + fr) * 272 + (k * 32 + fq * 8) * 2); yo = mfma16(cf[k], bb, yo); }
; { const f32x4 a4 = *(const f32x4*)(acP + lt * 16 + fq * 4);
; #pragma unroll
;               for (int j = 0; j < 4; ++j) yo[j] *= __expf(a4[j]); }
;             const float acl_fr = acP[lt * 16 + fr]; const int lrow = lt * 16 + fr;
; #pragma unroll
;             for (int t = 0; t < 2; ++t) {
;                 if (2 * t <= lt) {
;                     v2u xb0, xb1;
;                     { const unsigned a0 = lds0 + par * T_BUF + T_XD + (32 * t + 4 * fq + tq) * 80 + (pt * 16 + 4 * tp) * 2, a1 = a0 + 16 * 80; TR_ISSUE(xb0, a0); TR_ISSUE(xb1, a1); }
;                     float m[8];
.Lssd_loop3:
	ds_read_b128 v[28:31], v219 offset:12288
	ds_read_b128 v[32:35], v220 offset:12288
	ds_read_b128 v[40:43], v221 offset:12288
	ds_read_b128 v[44:47], v222 offset:12288
	ds_read_b128 v[48:51], v227
	ds_read_b128 v[52:55], v228
	ds_read_b128 v[56:59], v229
	ds_read_b128 v[60:63], v230
	ds_read_b32 v194, v231 offset:192
	ds_read_b128 v[64:67], v219 offset:16384
	ds_read_b128 v[68:71], v220 offset:16384
	ds_read_b128 v[72:75], v221 offset:16384
	ds_read_b128 v[76:79], v222 offset:16384
	ds_read_b128 v[80:83], v219 offset:20480
	ds_read_b128 v[84:87], v220 offset:20480
	global_load_dwordx4 v[140:143], v204, s[40:41] offset:2048
	s_waitcnt lgkmcnt(11)
	ds_read_b128 v[88:91], v221 offset:20480
	ds_read_b128 v[92:95], v222 offset:20480
	ds_read_b128 v[96:99], v232
	global_load_dwordx4 v[144:147], v205, s[40:41] offset:2048
	ds_read_b128 v[100:103], v232 offset:64
	s_waitcnt lgkmcnt(11)
	ds_read_b64 v[124:125], v235 offset:46464
	ds_read_b64 v[126:127], v235 offset:51072
	global_load_dwordx4 v[132:135], v204, s[40:41]
	v_mfma_f32_16x16x32_bf16 v[24:27], v[48:51], v[28:31], 0
	v_mfma_f32_16x16x32_bf16 v[24:27], v[52:55], v[32:35], v[24:27]
	v_mfma_f32_16x16x32_bf16 v[24:27], v[56:59], v[40:43], v[24:27]
	global_load_dwordx4 v[136:139], v205, s[40:41]
	v_mfma_f32_16x16x32_bf16 v[24:27], v[60:63], v[44:47], v[24:27]
	ds_read_b64_tr_b16 v[56:57], v233 offset:32768
	ds_read_b64_tr_b16 v[58:59], v233 offset:34048
	global_load_dwordx2 v[4:5], v206, s[40:41]
	s_waitcnt lgkmcnt(13)
	v_mfma_f32_16x16x32_bf16 v[48:51], v[64:67], v[28:31], 0
	s_waitcnt lgkmcnt(9)
	v_mfma_f32_16x16x32_bf16 v[52:55], v[80:83], v[28:31], 0
	v_mfma_f32_16x16x32_bf16 v[48:51], v[68:71], v[32:35], v[48:51]
	s_waitcnt lgkmcnt(8)
	v_mfma_f32_16x16x32_bf16 v[52:55], v[84:87], v[32:35], v[52:55]
	global_load_dwordx2 v[36:37], v207, s[42:43] nt
	v_mfma_f32_16x16x32_bf16 v[48:51], v[72:75], v[40:43], v[48:51]
	s_waitcnt lgkmcnt(7)
	v_mfma_f32_16x16x32_bf16 v[52:55], v[88:91], v[40:43], v[52:55]
	v_mfma_f32_16x16x32_bf16 v[48:51], v[76:79], v[44:47], v[48:51]
	global_load_dword v6, v208, s[44:45]
	s_waitcnt lgkmcnt(6)
	v_mfma_f32_16x16x32_bf16 v[52:55], v[92:95], v[44:47], v[52:55]
	ds_read_b128 v[64:67], v219 offset:24576
	ds_read_b128 v[68:71], v220 offset:24576
	global_load_dword v116, v208, s[46:47]
	ds_read_b128 v[72:75], v221 offset:24576
	ds_read_b128 v[76:79], v222 offset:24576
	ds_read_b128 v[80:83], v219 offset:28672
	global_load_dword v117, v209, s[46:47]
	ds_read_b128 v[84:87], v220 offset:28672
	ds_read_b128 v[88:91], v221 offset:28672
	ds_read_b128 v[92:95], v222 offset:28672
	s_add_u32 s66, s54, 3
	s_cmp_lt_u32 s66, s39
	s_cselect_b32 s74, 0xc0000, 0
	s_cselect_b32 s75, 0x280000, 0
	s_cselect_b32 s76, 0x4000, 0
	s_add_u32 s40, s40, s74
	s_addc_u32 s41, s41, 0
	s_add_u32 s42, s42, s75
	s_addc_u32 s43, s43, 0
	s_add_u32 s44, s44, s76
	s_addc_u32 s45, s45, 0
	s_add_u32 s46, s46, s76
	s_addc_u32 s47, s47, 0
	ds_read_b64_tr_b16 v[60:61], v233 offset:35328
	s_waitcnt lgkmcnt(11)
	ds_read_b64_tr_b16 v[62:63], v233 offset:36608
	v_exp_f32_e32 v195, v194
	s_nop 0
	v_mul_f32_e32 v24, v24, v195
	v_mul_f32_e32 v25, v25, v195
	v_mul_f32_e32 v26, v26, v195
	v_mul_f32_e32 v27, v27, v195
	v_lshlrev_b32_e32 v112, 16, v126
	v_and_b32_e32 v113, 0xffff0000, v126
	v_lshlrev_b32_e32 v114, 16, v127
	v_and_b32_e32 v115, 0xffff0000, v127
	v_mul_f32_e32 v120, 0xbfb8aa3b, v112
	v_mul_f32_e32 v121, 0xbfb8aa3b, v113
	v_mul_f32_e32 v122, 0xbfb8aa3b, v114
	v_mul_f32_e32 v123, 0xbfb8aa3b, v115
	v_exp_f32_e32 v120, v120
	v_exp_f32_e32 v121, v121
	v_exp_f32_e32 v122, v122
	v_exp_f32_e32 v123, v123
	v_add_f32_e32 v120, 1.0, v120
	v_add_f32_e32 v121, 1.0, v121
	v_add_f32_e32 v122, 1.0, v122
	v_add_f32_e32 v123, 1.0, v123
	v_rcp_f32_e32 v120, v120
	v_rcp_f32_e32 v121, v121
	v_rcp_f32_e32 v122, v122
	v_rcp_f32_e32 v123, v123
	v_mul_f32_e32 v112, v120, v112
	v_mul_f32_e32 v113, v121, v113
	v_mul_f32_e32 v114, v122, v114
	v_mul_f32_e32 v115, v123, v115
	v_lshlrev_b32_e32 v120, 16, v124
	v_and_b32_e32 v121, 0xffff0000, v124
	v_lshlrev_b32_e32 v122, 16, v125
	v_and_b32_e32 v123, 0xffff0000, v125
	v_sub_f32_e32 v184, v194, v96
	v_sub_f32_e32 v185, v194, v97
	v_sub_f32_e32 v186, v194, v98
	v_sub_f32_e32 v187, v194, v99
	v_exp_f32_e32 v184, v184
	v_exp_f32_e32 v185, v185
	v_exp_f32_e32 v186, v186
	v_exp_f32_e32 v187, v187
	v_mul_f32_e32 v184, v48, v184
	v_mul_f32_e32 v185, v49, v185
	v_mul_f32_e32 v186, v50, v186
	v_mul_f32_e32 v187, v51, v187
	v_sub_f32_e32 v188, v194, v100
	v_sub_f32_e32 v189, v194, v101
	v_sub_f32_e32 v190, v194, v102
	v_sub_f32_e32 v191, v194, v103
	v_exp_f32_e32 v188, v188
	v_exp_f32_e32 v189, v189
	s_waitcnt vmcnt(10)
	v_exp_f32_e32 v190, v190
	v_exp_f32_e32 v191, v191
	ds_write_b128 v213, v[156:159]
	v_mul_f32_e32 v188, v52, v188
	ds_write_b128 v213, v[160:163] offset:8192
	v_mul_f32_e32 v189, v53, v189
	v_mul_f32_e32 v190, v54, v190
	ds_write_b128 v213, v[148:151] offset:16384
	v_mul_f32_e32 v191, v55, v191
	v_cvt_pk_bf16_f32 v128, v184, v185
	s_waitcnt lgkmcnt(11)
	ds_write_b128 v213, v[152:155] offset:24576
	v_cvt_pk_bf16_f32 v129, v186, v187
	v_sub_f32_e32 v200, v169, v168
	v_cvt_pk_bf16_f32 v130, v188, v189
	v_cvt_pk_bf16_f32 v131, v190, v191
	v_mul_f32_e32 v200, 0x3fb8aa3b, v200
	s_nop 0
	v_mfma_f32_16x16x32_bf16 v[24:27], v[56:59], v[128:131], v[24:27]
	v_exp_f32_e32 v200, v200
	ds_read_b128 v[96:99], v232 offset:128
	ds_read_b128 v[100:103], v232 offset:192
	v_lshlrev_b32_e32 v196, 16, v164
	v_mfma_f32_16x16x32_bf16 v[48:51], v[64:67], v[28:31], 0
	s_waitcnt lgkmcnt(11)
; __device__ __forceinline__ void phase_ssd(const Params& P, int seg, unsigned char* smem) {
;     ...
;         auto step = [&](int ci, Pre& R, const int par) {
;             const int row0 = chunk_row0(ci); unsigned char* sb = smem + par * T_BUF; float* acP = acS + par * 64;
;             const bf16* StR = StS + par * (T_STSZ / 2); bf16* StW = StS + (par ^ 1) * (T_STSZ / 2);
;             const float dec = __expf(R.alast);
;             { const float e2 = __expf(R.alast - R.acl);
; #pragma unroll
;               for (int i = 0; i < 2; ++i) { const int q = tid + 512 * i, l = q >> 4, c8 = q & 15; *(v4u*)(sb + T_CS + l * 272 + c8 * 16) = R.Cr[i]; *(v4u*)(sb + T_BS + l * 272 + c8 * 16) = R.Br[i]; }
;               const int l = tid >> 3, p4 = (tid & 7) * 4;
;               const float x0 = bflo(R.Xr.x) * R.dtl, x1 = bfhi(R.Xr.x) * R.dtl, x2 = bflo(R.Xr.y) * R.dtl, x3 = bfhi(R.Xr.y) * R.dtl;
;               v2u d; d.x = cvt_pk_bf16(x0, x1); d.y = cvt_pk_bf16(x2, x3); *(v2u*)(sb + T_XD + l * 80 + p4 * 2) = d;
;               v2u e; e.x = cvt_pk_bf16(x0 * e2, x1 * e2); e.y = cvt_pk_bf16(x2 * e2, x3 * e2); *(v2u*)(sb + T_XE + l * 80 + p4 * 2) = e;
;               *(v2u*)(sb + T_XS + l * 64 + p4 * 2) = R.Xr; *(v2u*)(sb + T_ZS + l * 64 + p4 * 2) = R.Zr;
;               if (w == 0) acP[lane] = R.aclane; }
;             BAR_LDS();
;             if (ci + 2 < nchunks) load_chunk(ci + 2, R);
;             bf16x8 cf[4];
; #pragma unroll
;             for (int k = 0; k < 4; ++k) cf[k] = *(const bf16x8*)(sb + T_CS + (lt * 16 + fr) * 272 + (k * 32 + fq * 8) * 2);
;             f32x4 yo = {0.f, 0.f, 0.f, 0.f};
; #pragma unroll
;             for (int k = 0; k < 4; ++k) { const bf16x8 bb = *(const bf16x8*)((const unsigned char*)StR + (pt * 16 + fr) * 272 + (k * 32 + fq * 8) * 2); yo = mfma16(cf[k], bb, yo); }
; { const f32x4 a4 = *(const f32x4*)(acP + lt * 16 + fq * 4);
; #pragma unroll
;               for (int j = 0; j < 4; ++j) yo[j] *= __expf(a4[j]); }
;             const float acl_fr = acP[lt * 16 + fr]; const int lrow = lt * 16 + fr;
; #pragma unroll
;             for (int t = 0; t < 2; ++t) {
;                 if (2 * t <= lt) {
;                     v2u xb0, xb1;
;                     { const unsigned a0 = lds0 + par * T_BUF + T_XD + (32 * t + 4 * fq + tq) * 80 + (pt * 16 + 4 * tp) * 2, a1 = a0 + 16 * 80; TR_ISSUE(xb0, a0); TR_ISSUE(xb1, a1); }
;                     float m[8];
	v_mfma_f32_16x16x32_bf16 v[52:55], v[80:83], v[28:31], 0
	v_and_b32_e32 v197, 0xffff0000, v164
	v_mfma_f32_16x16x32_bf16 v[48:51], v[68:71], v[32:35], v[48:51]
	v_lshlrev_b32_e32 v198, 16, v165
	s_waitcnt lgkmcnt(10)
	v_mfma_f32_16x16x32_bf16 v[52:55], v[84:87], v[32:35], v[52:55]
	v_mfma_f32_16x16x32_bf16 v[48:51], v[72:75], v[40:43], v[48:51]
	v_and_b32_e32 v199, 0xffff0000, v165
	s_waitcnt lgkmcnt(9)
	v_mfma_f32_16x16x32_bf16 v[52:55], v[88:91], v[40:43], v[52:55]
	v_mul_f32_e32 v196, v196, v118
	v_mfma_f32_16x16x32_bf16 v[48:51], v[76:79], v[44:47], v[48:51]
	s_waitcnt lgkmcnt(8)
	v_mfma_f32_16x16x32_bf16 v[52:55], v[92:95], v[44:47], v[52:55]
	v_mul_f32_e32 v197, v197, v118
	s_waitcnt lgkmcnt(1)
	v_sub_f32_e32 v184, v194, v96
	v_sub_f32_e32 v185, v194, v97
	v_mul_f32_e32 v198, v198, v118
	v_sub_f32_e32 v186, v194, v98
	v_mul_f32_e32 v199, v199, v118
	v_sub_f32_e32 v187, v194, v99
	v_exp_f32_e32 v184, v184
	v_cvt_pk_bf16_f32 v202, v196, v197
	v_exp_f32_e32 v185, v185
	v_cvt_pk_bf16_f32 v203, v198, v199
	v_exp_f32_e32 v186, v186
	v_exp_f32_e32 v187, v187
	ds_write_b64 v215, v[202:203] offset:32768
	v_mul_f32_e32 v184, v48, v184
	v_mul_f32_e32 v185, v49, v185
	v_mul_f32_e32 v196, v196, v200
	v_mul_f32_e32 v186, v50, v186
	v_mul_f32_e32 v197, v197, v200
	v_mul_f32_e32 v187, v51, v187
	s_waitcnt lgkmcnt(1)
	v_sub_f32_e32 v188, v194, v100
	v_mul_f32_e32 v198, v198, v200
	v_sub_f32_e32 v189, v194, v101
	v_mul_f32_e32 v199, v199, v200
	v_sub_f32_e32 v190, v194, v102
	v_sub_f32_e32 v191, v194, v103
	v_cvt_pk_bf16_f32 v192, v196, v197
	v_exp_f32_e32 v188, v188
	v_exp_f32_e32 v189, v189
	v_cvt_pk_bf16_f32 v193, v198, v199
	v_exp_f32_e32 v190, v190
	ds_write_b64 v215, v[192:193] offset:37888
	v_exp_f32_e32 v191, v191
	v_mul_f32_e32 v188, v52, v188
	ds_write_b64 v217, v[164:165] offset:43008
	v_mul_f32_e32 v189, v53, v189
	ds_write_b64 v217, v[166:167] offset:47616
	v_mul_f32_e32 v190, v54, v190
	v_mul_f32_e32 v191, v55, v191
	v_mul_f32_e32 v201, 0x3fb8aa3b, v168
	v_cndmask_b32_e64 v188, 0, v188, s[14:15]
	v_cndmask_b32_e64 v189, 0, v189, s[16:17]
	ds_write_b32 v218, v201 offset:256
	v_cndmask_b32_e64 v190, 0, v190, s[22:23]
	v_mul_f32_e32 v174, 0x3fb8aa3b, v169
	v_cndmask_b32_e64 v191, 0, v191, s[34:35]
	v_cvt_pk_bf16_f32 v128, v184, v185
	v_exp_f32_e32 v174, v174
	v_cvt_pk_bf16_f32 v129, v186, v187
	v_cvt_pk_bf16_f32 v130, v188, v189
	v_cvt_pk_bf16_f32 v131, v190, v191
	s_nop 1
	v_mfma_f32_16x16x32_bf16 v[24:27], v[60:63], v[128:131], v[24:27]
	s_mul_i32 s65, s56, 0x2000
	s_add_u32 s65, s65, 0x304f1000
	s_add_u32 s48, s0, s65
	s_addc_u32 s49, s1, 0
	s_nop 3
	v_fma_f32 v184, s61, v120, v24
	v_fma_f32 v185, s61, v121, v25
	v_fma_f32 v186, s61, v122, v26
	v_fma_f32 v187, s61, v123, v27
	v_mul_f32_e32 v184, v184, v112
	v_mul_f32_e32 v185, v185, v113
	v_mul_f32_e32 v186, v186, v114
	v_mul_f32_e32 v187, v187, v115
	v_cvt_pk_bf16_f32 v170, v184, v185
	v_cvt_pk_bf16_f32 v171, v186, v187
	global_store_dwordx2 v210, v[170:171], s[48:49]
	s_add_u32 s65, s54, 1
	s_sub_u32 s65, s65, s60
	s_lshl_b32 s65, s65, 6
	s_add_u32 s56, s65, s20
	s_waitcnt lgkmcnt(0)
	s_barrier
	s_add_u32 s54, s54, 1
	s_cmp_ge_u32 s54, s39
	s_cbranch_scc1 .Lssd_done
	ds_read_b128 v[28:31], v223 offset:12288
	ds_read_b128 v[32:35], v224 offset:12288
	ds_read_b128 v[40:43], v225 offset:12288
	ds_read_b128 v[44:47], v226 offset:12288
	ds_read_b128 v[48:51], v227 offset:8192
	ds_read_b128 v[52:55], v228 offset:8192
	ds_read_b128 v[56:59], v229 offset:8192
	ds_read_b128 v[60:63], v230 offset:8192
	ds_read_b32 v194, v231 offset:448
	ds_read_b128 v[64:67], v223 offset:16384
	ds_read_b128 v[68:71], v224 offset:16384
	ds_read_b128 v[72:75], v225 offset:16384
	ds_read_b128 v[76:79], v226 offset:16384
	ds_read_b128 v[80:83], v223 offset:20480
	ds_read_b128 v[84:87], v224 offset:20480
	global_load_dwordx4 v[156:159], v204, s[40:41] offset:2048
	s_waitcnt lgkmcnt(11)
	ds_read_b128 v[88:91], v225 offset:20480
	ds_read_b128 v[92:95], v226 offset:20480
	ds_read_b128 v[96:99], v232 offset:256
	global_load_dwordx4 v[160:163], v205, s[40:41] offset:2048
	ds_read_b128 v[100:103], v232 offset:320
	s_waitcnt lgkmcnt(11)
	ds_read_b64 v[124:125], v236 offset:46464
	ds_read_b64 v[126:127], v236 offset:51072
	global_load_dwordx4 v[148:151], v204, s[40:41]
	v_mfma_f32_16x16x32_bf16 v[24:27], v[48:51], v[28:31], 0
	v_mfma_f32_16x16x32_bf16 v[24:27], v[52:55], v[32:35], v[24:27]
	v_mfma_f32_16x16x32_bf16 v[24:27], v[56:59], v[40:43], v[24:27]
	global_load_dwordx4 v[152:155], v205, s[40:41]
	v_mfma_f32_16x16x32_bf16 v[24:27], v[60:63], v[44:47], v[24:27]
	ds_read_b64_tr_b16 v[56:57], v234 offset:32768
	ds_read_b64_tr_b16 v[58:59], v234 offset:34048
	global_load_dwordx2 v[164:165], v206, s[40:41]
	s_waitcnt lgkmcnt(13)
	v_mfma_f32_16x16x32_bf16 v[48:51], v[64:67], v[28:31], 0
	s_waitcnt lgkmcnt(9)
	v_mfma_f32_16x16x32_bf16 v[52:55], v[80:83], v[28:31], 0
	v_mfma_f32_16x16x32_bf16 v[48:51], v[68:71], v[32:35], v[48:51]
	s_waitcnt lgkmcnt(8)
	v_mfma_f32_16x16x32_bf16 v[52:55], v[84:87], v[32:35], v[52:55]
	global_load_dwordx2 v[166:167], v207, s[42:43] nt
	v_mfma_f32_16x16x32_bf16 v[48:51], v[72:75], v[40:43], v[48:51]
	s_waitcnt lgkmcnt(7)
	v_mfma_f32_16x16x32_bf16 v[52:55], v[88:91], v[40:43], v[52:55]
	v_mfma_f32_16x16x32_bf16 v[48:51], v[76:79], v[44:47], v[48:51]
	global_load_dword v118, v208, s[44:45]
	s_waitcnt lgkmcnt(6)
; __device__ __forceinline__ void phase_ssd(const Params& P, int seg, unsigned char* smem) {
;     ...
;         auto load_chunk = [&](int ci, Pre& R) { const int row0 = chunk_row0(ci);
; #pragma unroll
;             for (int i = 0; i < 2; ++i) { const int q = tid + 512 * i, l = q >> 4, c8 = q & 15; const GAS bf16* rp = xconv + (size_t)(row0 + l) * DXBC + g * 128 + c8 * 8;
;                 R.Br[i] = *(const GAS v4u*)(rp + 4096); R.Cr[i] = *(const GAS v4u*)(rp + 5120); }
;             { const int l = tid >> 3, p4 = (tid & 7) * 4; R.Xr = *(const GAS v2u*)(xconv + (size_t)(row0 + l) * DXBC + h * 64 + ph * 32 + p4);
;               R.Zr = __builtin_nontemporal_load((const GAS v2u*)(proj + (size_t)(row0 + l) * NPROJ + OFF_Z + h * 64 + ph * 32 + p4));
;               R.dtl = dtv[(size_t)(row0 + l) * 64 + h]; R.acl = acv[(size_t)(row0 + l) * 64 + h]; }
;             R.alast = acv[(size_t)(row0 + 63) * 64 + h]; R.aclane = acv[(size_t)(row0 + lane) * 64 + h]; };
;         load_chunk(0, RA); if (nchunks > 1) load_chunk(1, RB);
;         auto step = [&](int ci, Pre& R, const int par) {
;             const int row0 = chunk_row0(ci); unsigned char* sb = smem + par * T_BUF; float* acP = acS + par * 64;
;             const bf16* StR = StS + par * (T_STSZ / 2); bf16* StW = StS + (par ^ 1) * (T_STSZ / 2);
;             const float dec = __expf(R.alast);
;             { const float e2 = __expf(R.alast - R.acl);
; #pragma unroll
;               for (int i = 0; i < 2; ++i) { const int q = tid + 512 * i, l = q >> 4, c8 = q & 15; *(v4u*)(sb + T_CS + l * 272 + c8 * 16) = R.Cr[i]; *(v4u*)(sb + T_BS + l * 272 + c8 * 16) = R.Br[i]; }
;               const int l = tid >> 3, p4 = (tid & 7) * 4;
;               const float x0 = bflo(R.Xr.x) * R.dtl, x1 = bfhi(R.Xr.x) * R.dtl, x2 = bflo(R.Xr.y) * R.dtl, x3 = bfhi(R.Xr.y) * R.dtl;
;               v2u d; d.x = cvt_pk_bf16(x0, x1); d.y = cvt_pk_bf16(x2, x3); *(v2u*)(sb + T_XD + l * 80 + p4 * 2) = d;
;               v2u e; e.x = cvt_pk_bf16(x0 * e2, x1 * e2); e.y = cvt_pk_bf16(x2 * e2, x3 * e2); *(v2u*)(sb + T_XE + l * 80 + p4 * 2) = e;
;               *(v2u*)(sb + T_XS + l * 64 + p4 * 2) = R.Xr; *(v2u*)(sb + T_ZS + l * 64 + p4 * 2) = R.Zr;
;               if (w == 0) acP[lane] = R.aclane; }
;             BAR_LDS();
;             if (ci + 2 < nchunks) load_chunk(ci + 2, R);
;             bf16x8 cf[4];
; #pragma unroll
	v_mfma_f32_16x16x32_bf16 v[52:55], v[92:95], v[44:47], v[52:55]
	ds_read_b128 v[64:67], v223 offset:24576
	ds_read_b128 v[68:71], v224 offset:24576
	global_load_dword v168, v208, s[46:47]
	ds_read_b128 v[72:75], v225 offset:24576
	ds_read_b128 v[76:79], v226 offset:24576
	ds_read_b128 v[80:83], v223 offset:28672
	global_load_dword v169, v209, s[46:47]
	ds_read_b128 v[84:87], v224 offset:28672
	ds_read_b128 v[88:91], v225 offset:28672
	ds_read_b128 v[92:95], v226 offset:28672
	s_add_u32 s66, s54, 3
	s_cmp_lt_u32 s66, s39
	s_cselect_b32 s74, 0xc0000, 0
	s_cselect_b32 s75, 0x280000, 0
	s_cselect_b32 s76, 0x4000, 0
	s_add_u32 s40, s40, s74
	s_addc_u32 s41, s41, 0
	s_add_u32 s42, s42, s75
	s_addc_u32 s43, s43, 0
	s_add_u32 s44, s44, s76
	s_addc_u32 s45, s45, 0
	s_add_u32 s46, s46, s76
	s_addc_u32 s47, s47, 0
	ds_read_b64_tr_b16 v[60:61], v234 offset:35328
	s_waitcnt lgkmcnt(11)
	ds_read_b64_tr_b16 v[62:63], v234 offset:36608
	v_exp_f32_e32 v195, v194
	s_nop 0
	v_mul_f32_e32 v24, v24, v195
	v_mul_f32_e32 v25, v25, v195
	v_mul_f32_e32 v26, v26, v195
	v_mul_f32_e32 v27, v27, v195
	v_lshlrev_b32_e32 v112, 16, v126
	v_and_b32_e32 v113, 0xffff0000, v126
	v_lshlrev_b32_e32 v114, 16, v127
	v_and_b32_e32 v115, 0xffff0000, v127
	v_mul_f32_e32 v120, 0xbfb8aa3b, v112
	v_mul_f32_e32 v121, 0xbfb8aa3b, v113
	v_mul_f32_e32 v122, 0xbfb8aa3b, v114
	v_mul_f32_e32 v123, 0xbfb8aa3b, v115
	v_exp_f32_e32 v120, v120
	v_exp_f32_e32 v121, v121
	v_exp_f32_e32 v122, v122
	v_exp_f32_e32 v123, v123
	v_add_f32_e32 v120, 1.0, v120
	v_add_f32_e32 v121, 1.0, v121
	v_add_f32_e32 v122, 1.0, v122
	v_add_f32_e32 v123, 1.0, v123
	v_rcp_f32_e32 v120, v120
	v_rcp_f32_e32 v121, v121
	v_rcp_f32_e32 v122, v122
	v_rcp_f32_e32 v123, v123
	v_mul_f32_e32 v112, v120, v112
	v_mul_f32_e32 v113, v121, v113
	v_mul_f32_e32 v114, v122, v114
	v_mul_f32_e32 v115, v123, v115
	v_lshlrev_b32_e32 v120, 16, v124
	v_and_b32_e32 v121, 0xffff0000, v124
	v_lshlrev_b32_e32 v122, 16, v125
	v_and_b32_e32 v123, 0xffff0000, v125
	v_sub_f32_e32 v184, v194, v96
	v_sub_f32_e32 v185, v194, v97
	v_sub_f32_e32 v186, v194, v98
	v_sub_f32_e32 v187, v194, v99
	v_exp_f32_e32 v184, v184
	v_exp_f32_e32 v185, v185
	v_exp_f32_e32 v186, v186
	v_exp_f32_e32 v187, v187
	v_mul_f32_e32 v184, v48, v184
	v_mul_f32_e32 v185, v49, v185
	v_mul_f32_e32 v186, v50, v186
	v_mul_f32_e32 v187, v51, v187
	v_sub_f32_e32 v188, v194, v100
	v_sub_f32_e32 v189, v194, v101
	v_sub_f32_e32 v190, v194, v102
	v_sub_f32_e32 v191, v194, v103
	v_exp_f32_e32 v188, v188
	v_exp_f32_e32 v189, v189
	s_waitcnt vmcnt(10)
	v_exp_f32_e32 v190, v190
	v_exp_f32_e32 v191, v191
	ds_write_b128 v212, v[140:143]
	v_mul_f32_e32 v188, v52, v188
	ds_write_b128 v212, v[144:147] offset:8192
	v_mul_f32_e32 v189, v53, v189
	v_mul_f32_e32 v190, v54, v190
	ds_write_b128 v212, v[132:135] offset:16384
	v_mul_f32_e32 v191, v55, v191
	v_cvt_pk_bf16_f32 v128, v184, v185
	s_waitcnt lgkmcnt(11)
	ds_write_b128 v212, v[136:139] offset:24576
	v_cvt_pk_bf16_f32 v129, v186, v187
	v_sub_f32_e32 v200, v117, v116
	v_cvt_pk_bf16_f32 v130, v188, v189
	v_cvt_pk_bf16_f32 v131, v190, v191
	v_mul_f32_e32 v200, 0x3fb8aa3b, v200
	s_nop 0
	v_mfma_f32_16x16x32_bf16 v[24:27], v[56:59], v[128:131], v[24:27]
	v_exp_f32_e32 v200, v200
	ds_read_b128 v[96:99], v232 offset:384
	ds_read_b128 v[100:103], v232 offset:448
	v_lshlrev_b32_e32 v196, 16, v4
	v_mfma_f32_16x16x32_bf16 v[48:51], v[64:67], v[28:31], 0
	s_waitcnt lgkmcnt(11)
	v_mfma_f32_16x16x32_bf16 v[52:55], v[80:83], v[28:31], 0
	v_and_b32_e32 v197, 0xffff0000, v4
	v_mfma_f32_16x16x32_bf16 v[48:51], v[68:71], v[32:35], v[48:51]
	v_lshlrev_b32_e32 v198, 16, v5
	s_waitcnt lgkmcnt(10)
	v_mfma_f32_16x16x32_bf16 v[52:55], v[84:87], v[32:35], v[52:55]
	v_mfma_f32_16x16x32_bf16 v[48:51], v[72:75], v[40:43], v[48:51]
	v_and_b32_e32 v199, 0xffff0000, v5
	s_waitcnt lgkmcnt(9)
	v_mfma_f32_16x16x32_bf16 v[52:55], v[88:91], v[40:43], v[52:55]
	v_mul_f32_e32 v196, v196, v6
	v_mfma_f32_16x16x32_bf16 v[48:51], v[76:79], v[44:47], v[48:51]
	s_waitcnt lgkmcnt(8)
	v_mfma_f32_16x16x32_bf16 v[52:55], v[92:95], v[44:47], v[52:55]
	v_mul_f32_e32 v197, v197, v6
	s_waitcnt lgkmcnt(1)
	v_sub_f32_e32 v184, v194, v96
	v_sub_f32_e32 v185, v194, v97
	v_mul_f32_e32 v198, v198, v6
	v_sub_f32_e32 v186, v194, v98
	v_mul_f32_e32 v199, v199, v6
	v_sub_f32_e32 v187, v194, v99
	v_exp_f32_e32 v184, v184
	v_cvt_pk_bf16_f32 v202, v196, v197
	v_exp_f32_e32 v185, v185
	v_cvt_pk_bf16_f32 v203, v198, v199
	v_exp_f32_e32 v186, v186
	v_exp_f32_e32 v187, v187
	ds_write_b64 v214, v[202:203] offset:32768
	v_mul_f32_e32 v184, v48, v184
	v_mul_f32_e32 v185, v49, v185
	v_mul_f32_e32 v196, v196, v200
	v_mul_f32_e32 v186, v50, v186
	v_mul_f32_e32 v197, v197, v200
	v_mul_f32_e32 v187, v51, v187
	s_waitcnt lgkmcnt(1)
	v_sub_f32_e32 v188, v194, v100
	v_mul_f32_e32 v198, v198, v200
	v_sub_f32_e32 v189, v194, v101
	v_mul_f32_e32 v199, v199, v200
	v_sub_f32_e32 v190, v194, v102
	v_sub_f32_e32 v191, v194, v103
	v_cvt_pk_bf16_f32 v192, v196, v197
	v_exp_f32_e32 v188, v188
	v_exp_f32_e32 v189, v189
	v_cvt_pk_bf16_f32 v193, v198, v199
	v_exp_f32_e32 v190, v190
	ds_write_b64 v214, v[192:193] offset:37888
	v_exp_f32_e32 v191, v191
	v_mul_f32_e32 v188, v52, v188
	ds_write_b64 v216, v[4:5] offset:43008
	v_mul_f32_e32 v189, v53, v189
	ds_write_b64 v216, v[36:37] offset:47616
	v_mul_f32_e32 v190, v54, v190
	v_mul_f32_e32 v191, v55, v191
	v_mul_f32_e32 v201, 0x3fb8aa3b, v116
	v_cndmask_b32_e64 v188, 0, v188, s[14:15]
	v_cndmask_b32_e64 v189, 0, v189, s[16:17]
	ds_write_b32 v218, v201
	v_cndmask_b32_e64 v190, 0, v190, s[22:23]
	v_mul_f32_e32 v174, 0x3fb8aa3b, v117
	v_cndmask_b32_e64 v191, 0, v191, s[34:35]
	v_cvt_pk_bf16_f32 v128, v184, v185
	v_exp_f32_e32 v174, v174
	v_cvt_pk_bf16_f32 v129, v186, v187
	v_cvt_pk_bf16_f32 v130, v188, v189
	v_cvt_pk_bf16_f32 v131, v190, v191
	s_nop 1
	v_mfma_f32_16x16x32_bf16 v[24:27], v[60:63], v[128:131], v[24:27]
	s_mul_i32 s65, s56, 0x2000
	s_add_u32 s65, s65, 0x304f1000
	s_add_u32 s48, s0, s65
	s_addc_u32 s49, s1, 0
	s_nop 3
	v_fma_f32 v184, s61, v120, v24
	v_fma_f32 v185, s61, v121, v25
	v_fma_f32 v186, s61, v122, v26
	v_fma_f32 v187, s61, v123, v27
	v_mul_f32_e32 v184, v184, v112
	v_mul_f32_e32 v185, v185, v113
	v_mul_f32_e32 v186, v186, v114
	v_mul_f32_e32 v187, v187, v115
	v_cvt_pk_bf16_f32 v170, v184, v185
	v_cvt_pk_bf16_f32 v171, v186, v187
	global_store_dwordx2 v210, v[170:171], s[48:49]
	s_add_u32 s65, s54, 1
	s_sub_u32 s65, s65, s60
	s_lshl_b32 s65, s65, 6
	s_add_u32 s56, s65, s20
	s_waitcnt lgkmcnt(0)
	s_barrier
	s_add_u32 s54, s54, 1
	s_cmp_lt_u32 s54, s39
	s_cbranch_scc1 .Lssd_loop3
